# K-loops: loop-control SALU moved before the iteration's last barrier (MFMA shadow); head DMA-address SALU block moved behind the first eight ds_reads
# baseline (speedup 1.0000x reference)
.LBB0_341:
	s_add_i32 s56, 0, 0x10000
	s_add_i32 s80, 0, 0x14000
	v_add_u32_e32 v102, s56, v171
	v_add_u32_e32 v177, s80, v171
	ds_read_b128 v[82:85], v102
	ds_read_b128 v[86:89], v102 offset:1024
	ds_read_b128 v[94:97], v102 offset:2048
	ds_read_b128 v[102:105], v102 offset:3072
	ds_read_b128 v[134:137], v177
	ds_read_b128 v[162:165], v177 offset:1024
	ds_read_b128 v[166:169], v177 offset:2048
	ds_read_b128 v[178:181], v177 offset:3072
	s_add_u32 s36, s34, 0xfffc0080
	s_addc_u32 s37, s35, -1
	s_cmp_eq_u32 s79, 12
	s_cselect_b32 s39, s25, s37
	s_cselect_b32 s38, s31, s36
	s_cselect_b32 s37, s23, s78
	s_cselect_b32 s36, s40, s77
	v_lshl_add_u64 v[214:215], s[34:35], 0, v[158:159]
	s_add_i32 m0, s9, 0xc000
	ds_read_b128 v[182:185], v176
	ds_read_b128 v[186:189], v176 offset:1024
	ds_read_b128 v[190:193], v176 offset:2048
	ds_read_b128 v[194:197], v176 offset:3072
	ds_read_b128 v[198:201], v176 offset:4096
	ds_read_b128 v[202:205], v176 offset:5120
	ds_read_b128 v[206:209], v176 offset:6144
	ds_read_b128 v[210:213], v176 offset:7168
	global_load_lds_dwordx4 v[214:215], off
	v_lshl_add_u64 v[214:215], s[34:35], 0, v[160:161]
	s_add_i32 m0, s9, 0xe000
	s_nop 0
	global_load_lds_dwordx4 v[214:215], off
	s_waitcnt vmcnt(8)
	s_waitcnt lgkmcnt(0)
	s_barrier
	s_waitcnt lgkmcnt(0)
	v_mfma_f32_16x16x32_bf16 v[146:149], v[82:85], v[182:185], v[146:149]
	v_mfma_f32_16x16x32_bf16 v[138:141], v[94:97], v[182:185], v[138:141]
	v_mfma_f32_16x16x32_bf16 v[126:129], v[82:85], v[190:193], v[126:129]
	v_mfma_f32_16x16x32_bf16 v[118:121], v[94:97], v[190:193], v[118:121]
	v_mfma_f32_16x16x32_bf16 v[110:113], v[82:85], v[198:201], v[110:113]
	v_mfma_f32_16x16x32_bf16 v[98:101], v[94:97], v[198:201], v[98:101]
	v_mfma_f32_16x16x32_bf16 v[78:81], v[82:85], v[206:209], v[78:81]
	v_mfma_f32_16x16x32_bf16 v[70:73], v[94:97], v[206:209], v[70:73]
	v_mfma_f32_16x16x32_bf16 v[146:149], v[86:89], v[186:189], v[146:149]
	v_mfma_f32_16x16x32_bf16 v[138:141], v[102:105], v[186:189], v[138:141]
	v_mfma_f32_16x16x32_bf16 v[126:129], v[86:89], v[194:197], v[126:129]
	v_mfma_f32_16x16x32_bf16 v[118:121], v[102:105], v[194:197], v[118:121]
	v_mfma_f32_16x16x32_bf16 v[110:113], v[86:89], v[202:205], v[110:113]
	v_mfma_f32_16x16x32_bf16 v[98:101], v[102:105], v[202:205], v[98:101]
	v_mfma_f32_16x16x32_bf16 v[78:81], v[86:89], v[210:213], v[78:81]
	v_mfma_f32_16x16x32_bf16 v[70:73], v[102:105], v[210:213], v[70:73]
	v_mfma_f32_16x16x32_bf16 v[142:145], v[134:137], v[182:185], v[142:145]
	v_mfma_f32_16x16x32_bf16 v[130:133], v[166:169], v[182:185], v[130:133]
	v_mfma_f32_16x16x32_bf16 v[122:125], v[134:137], v[190:193], v[122:125]
	v_mfma_f32_16x16x32_bf16 v[114:117], v[166:169], v[190:193], v[114:117]
	v_mfma_f32_16x16x32_bf16 v[106:109], v[134:137], v[198:201], v[106:109]
	v_mfma_f32_16x16x32_bf16 v[90:93], v[166:169], v[198:201], v[90:93]
	v_mfma_f32_16x16x32_bf16 v[74:77], v[134:137], v[206:209], v[74:77]
	v_mfma_f32_16x16x32_bf16 v[66:69], v[166:169], v[206:209], v[66:69]
	v_mfma_f32_16x16x32_bf16 v[142:145], v[162:165], v[186:189], v[142:145]
	v_mfma_f32_16x16x32_bf16 v[130:133], v[178:181], v[186:189], v[130:133]
	v_mfma_f32_16x16x32_bf16 v[122:125], v[162:165], v[194:197], v[122:125]
	v_mfma_f32_16x16x32_bf16 v[114:117], v[178:181], v[194:197], v[114:117]
	v_mfma_f32_16x16x32_bf16 v[106:109], v[162:165], v[202:205], v[106:109]
	v_mfma_f32_16x16x32_bf16 v[90:93], v[178:181], v[202:205], v[90:93]
	v_mfma_f32_16x16x32_bf16 v[74:77], v[162:165], v[210:213], v[74:77]
	v_mfma_f32_16x16x32_bf16 v[66:69], v[178:181], v[210:213], v[66:69]
	s_barrier
	s_add_i32 s56, s56, s68
	v_lshl_add_u64 v[214:215], s[36:37], 0, v[154:155]
	s_mov_b32 m0, s56
	ds_read_b128 v[182:185], v176 offset:16384
	ds_read_b128 v[186:189], v176 offset:17408
	ds_read_b128 v[190:193], v176 offset:18432
	ds_read_b128 v[194:197], v176 offset:19456
	ds_read_b128 v[198:201], v176 offset:20480
	ds_read_b128 v[202:205], v176 offset:21504
	ds_read_b128 v[206:209], v176 offset:22528
	ds_read_b128 v[210:213], v176 offset:23552
	global_load_lds_dwordx4 v[214:215], off
	s_add_i32 m0, s56, 0x2000
	s_add_u32 s56, s36, 0x40000
	v_lshl_add_u64 v[216:217], s[36:37], 0, v[156:157]
	s_addc_u32 s57, s37, 0
	s_add_i32 s80, s80, s68
	global_load_lds_dwordx4 v[216:217], off
	v_lshl_add_u64 v[218:219], s[56:57], 0, v[154:155]
	s_mov_b32 m0, s80
	v_lshl_add_u64 v[220:221], s[38:39], 0, v[152:153]
	global_load_lds_dwordx4 v[218:219], off
	v_lshl_add_u64 v[218:219], s[56:57], 0, v[156:157]
	s_add_i32 m0, s80, 0x2000
	s_nop 0
	global_load_lds_dwordx4 v[218:219], off
	v_lshl_add_u64 v[218:219], s[38:39], 0, v[150:151]
	s_mov_b32 m0, s9
	s_nop 0
	global_load_lds_dwordx4 v[218:219], off
	s_mov_b32 m0, s69
	s_nop 0
	global_load_lds_dwordx4 v[220:221], off
	s_waitcnt vmcnt(8)
	s_waitcnt lgkmcnt(0)
	s_barrier
	s_waitcnt lgkmcnt(0)
	v_mfma_f32_16x16x32_bf16 v[62:65], v[82:85], v[182:185], v[62:65]
	v_mfma_f32_16x16x32_bf16 v[54:57], v[94:97], v[182:185], v[54:57]
	v_mfma_f32_16x16x32_bf16 v[46:49], v[82:85], v[190:193], v[46:49]
	v_mfma_f32_16x16x32_bf16 v[38:41], v[94:97], v[190:193], v[38:41]
	v_mfma_f32_16x16x32_bf16 v[30:33], v[82:85], v[198:201], v[30:33]
	v_mfma_f32_16x16x32_bf16 v[22:25], v[94:97], v[198:201], v[22:25]
	v_mfma_f32_16x16x32_bf16 v[14:17], v[82:85], v[206:209], v[14:17]
	v_mfma_f32_16x16x32_bf16 v[6:9], v[94:97], v[206:209], v[6:9]
	v_mfma_f32_16x16x32_bf16 v[62:65], v[86:89], v[186:189], v[62:65]
	v_mfma_f32_16x16x32_bf16 v[54:57], v[102:105], v[186:189], v[54:57]
	v_mfma_f32_16x16x32_bf16 v[46:49], v[86:89], v[194:197], v[46:49]
	v_mfma_f32_16x16x32_bf16 v[38:41], v[102:105], v[194:197], v[38:41]
	v_mfma_f32_16x16x32_bf16 v[30:33], v[86:89], v[202:205], v[30:33]
	v_mfma_f32_16x16x32_bf16 v[22:25], v[102:105], v[202:205], v[22:25]
	v_mfma_f32_16x16x32_bf16 v[14:17], v[86:89], v[210:213], v[14:17]
	v_mfma_f32_16x16x32_bf16 v[6:9], v[102:105], v[210:213], v[6:9]
	v_mfma_f32_16x16x32_bf16 v[58:61], v[134:137], v[182:185], v[58:61]
	v_mfma_f32_16x16x32_bf16 v[50:53], v[166:169], v[182:185], v[50:53]
	v_mfma_f32_16x16x32_bf16 v[42:45], v[134:137], v[190:193], v[42:45]
	v_mfma_f32_16x16x32_bf16 v[34:37], v[166:169], v[190:193], v[34:37]
	v_mfma_f32_16x16x32_bf16 v[26:29], v[134:137], v[198:201], v[26:29]
	v_mfma_f32_16x16x32_bf16 v[18:21], v[166:169], v[198:201], v[18:21]
	v_mfma_f32_16x16x32_bf16 v[10:13], v[134:137], v[206:209], v[10:13]
	v_mfma_f32_16x16x32_bf16 v[2:5], v[166:169], v[206:209], v[2:5]
	v_mfma_f32_16x16x32_bf16 v[58:61], v[162:165], v[186:189], v[58:61]
	v_mfma_f32_16x16x32_bf16 v[50:53], v[178:181], v[186:189], v[50:53]
	v_mfma_f32_16x16x32_bf16 v[42:45], v[162:165], v[194:197], v[42:45]
	v_mfma_f32_16x16x32_bf16 v[34:37], v[178:181], v[194:197], v[34:37]
	v_mfma_f32_16x16x32_bf16 v[26:29], v[162:165], v[202:205], v[26:29]
	v_mfma_f32_16x16x32_bf16 v[18:21], v[178:181], v[202:205], v[18:21]
	v_mfma_f32_16x16x32_bf16 v[10:13], v[162:165], v[210:213], v[10:13]
	v_mfma_f32_16x16x32_bf16 v[2:5], v[178:181], v[210:213], v[2:5]
	s_barrier
	s_add_i32 s56, 0, 0x18000
	s_add_i32 s57, 0, 0x1c000
	v_add_u32_e32 v102, s56, v171
	v_add_u32_e32 v177, s57, v171
	ds_read_b128 v[82:85], v102
	ds_read_b128 v[86:89], v102 offset:1024
	ds_read_b128 v[94:97], v102 offset:2048
	ds_read_b128 v[102:105], v102 offset:3072
	ds_read_b128 v[134:137], v177
	ds_read_b128 v[162:165], v177 offset:1024
	ds_read_b128 v[166:169], v177 offset:2048
	ds_read_b128 v[178:181], v177 offset:3072
	s_add_u32 s38, s38, 0x40000
	s_addc_u32 s39, s39, 0
	s_mov_b32 m0, s70
	v_lshl_add_u64 v[232:233], s[38:39], 0, v[150:151]
	ds_read_b128 v[182:185], v176 offset:32768
	ds_read_b128 v[186:189], v176 offset:33792
	ds_read_b128 v[190:193], v176 offset:34816
	ds_read_b128 v[194:197], v176 offset:35840
	ds_read_b128 v[198:201], v176 offset:36864
	ds_read_b128 v[202:205], v176 offset:37888
	ds_read_b128 v[206:209], v176 offset:38912
	ds_read_b128 v[210:213], v176 offset:39936
	global_load_lds_dwordx4 v[232:233], off
	v_lshl_add_u64 v[232:233], s[38:39], 0, v[152:153]
	s_mov_b32 m0, s71
	s_nop 0
	global_load_lds_dwordx4 v[232:233], off
	s_waitcnt vmcnt(8)
	s_waitcnt lgkmcnt(0)
	s_barrier
	s_waitcnt lgkmcnt(0)
	v_mfma_f32_16x16x32_bf16 v[146:149], v[82:85], v[182:185], v[146:149]
	v_mfma_f32_16x16x32_bf16 v[138:141], v[94:97], v[182:185], v[138:141]
	v_mfma_f32_16x16x32_bf16 v[126:129], v[82:85], v[190:193], v[126:129]
	v_mfma_f32_16x16x32_bf16 v[118:121], v[94:97], v[190:193], v[118:121]
	v_mfma_f32_16x16x32_bf16 v[110:113], v[82:85], v[198:201], v[110:113]
	v_mfma_f32_16x16x32_bf16 v[98:101], v[94:97], v[198:201], v[98:101]
	v_mfma_f32_16x16x32_bf16 v[78:81], v[82:85], v[206:209], v[78:81]
	v_mfma_f32_16x16x32_bf16 v[70:73], v[94:97], v[206:209], v[70:73]
	v_mfma_f32_16x16x32_bf16 v[146:149], v[86:89], v[186:189], v[146:149]
	v_mfma_f32_16x16x32_bf16 v[138:141], v[102:105], v[186:189], v[138:141]
	v_mfma_f32_16x16x32_bf16 v[126:129], v[86:89], v[194:197], v[126:129]
	v_mfma_f32_16x16x32_bf16 v[118:121], v[102:105], v[194:197], v[118:121]
	v_mfma_f32_16x16x32_bf16 v[110:113], v[86:89], v[202:205], v[110:113]
	v_mfma_f32_16x16x32_bf16 v[98:101], v[102:105], v[202:205], v[98:101]
	v_mfma_f32_16x16x32_bf16 v[78:81], v[86:89], v[210:213], v[78:81]
	v_mfma_f32_16x16x32_bf16 v[70:73], v[102:105], v[210:213], v[70:73]
	v_mfma_f32_16x16x32_bf16 v[142:145], v[134:137], v[182:185], v[142:145]
	v_mfma_f32_16x16x32_bf16 v[130:133], v[166:169], v[182:185], v[130:133]
	v_mfma_f32_16x16x32_bf16 v[122:125], v[134:137], v[190:193], v[122:125]
	v_mfma_f32_16x16x32_bf16 v[114:117], v[166:169], v[190:193], v[114:117]
	v_mfma_f32_16x16x32_bf16 v[106:109], v[134:137], v[198:201], v[106:109]
	v_mfma_f32_16x16x32_bf16 v[90:93], v[166:169], v[198:201], v[90:93]
	v_mfma_f32_16x16x32_bf16 v[74:77], v[134:137], v[206:209], v[74:77]
	v_mfma_f32_16x16x32_bf16 v[66:69], v[166:169], v[206:209], v[66:69]
	v_mfma_f32_16x16x32_bf16 v[142:145], v[162:165], v[186:189], v[142:145]
	v_mfma_f32_16x16x32_bf16 v[130:133], v[178:181], v[186:189], v[130:133]
	v_mfma_f32_16x16x32_bf16 v[122:125], v[162:165], v[194:197], v[122:125]
	v_mfma_f32_16x16x32_bf16 v[114:117], v[178:181], v[194:197], v[114:117]
	v_mfma_f32_16x16x32_bf16 v[106:109], v[162:165], v[202:205], v[106:109]
	v_mfma_f32_16x16x32_bf16 v[90:93], v[178:181], v[202:205], v[90:93]
	v_mfma_f32_16x16x32_bf16 v[74:77], v[162:165], v[210:213], v[74:77]
	v_mfma_f32_16x16x32_bf16 v[66:69], v[178:181], v[210:213], v[66:69]
	s_barrier
	s_add_i32 s38, s56, s68
	v_lshl_add_u64 v[214:215], v[214:215], 0, s[62:63]
	s_mov_b32 m0, s38
	ds_read_b128 v[182:185], v176 offset:49152
	ds_read_b128 v[186:189], v176 offset:50176
	ds_read_b128 v[190:193], v176 offset:51200
	ds_read_b128 v[194:197], v176 offset:52224
	ds_read_b128 v[198:201], v176 offset:53248
	ds_read_b128 v[202:205], v176 offset:54272
	ds_read_b128 v[206:209], v176 offset:55296
	ds_read_b128 v[210:213], v176 offset:56320
	global_load_lds_dwordx4 v[214:215], off
	s_add_i32 m0, s38, 0x2000
	s_add_u32 s36, s36, 0x40080
	v_lshl_add_u64 v[214:215], v[216:217], 0, s[62:63]
	s_addc_u32 s37, s37, 0
	s_add_i32 s38, s57, s68
	global_load_lds_dwordx4 v[214:215], off
	v_lshl_add_u64 v[214:215], s[36:37], 0, v[154:155]
	s_mov_b32 m0, s38
	s_nop 0
	global_load_lds_dwordx4 v[214:215], off
	v_lshl_add_u64 v[214:215], s[36:37], 0, v[156:157]
	s_add_i32 m0, s38, 0x2000
	s_nop 0
	global_load_lds_dwordx4 v[214:215], off
	v_lshl_add_u64 v[214:215], v[218:219], 0, s[62:63]
	s_mov_b32 m0, s73
	s_nop 0
	global_load_lds_dwordx4 v[214:215], off
	v_lshl_add_u64 v[214:215], v[220:221], 0, s[62:63]
	s_mov_b32 m0, s74
	s_nop 0
	global_load_lds_dwordx4 v[214:215], off
	s_waitcnt vmcnt(8)
	s_waitcnt lgkmcnt(0)
	s_barrier
	s_waitcnt lgkmcnt(0)
	v_mfma_f32_16x16x32_bf16 v[62:65], v[82:85], v[182:185], v[62:65]
	v_mfma_f32_16x16x32_bf16 v[54:57], v[94:97], v[182:185], v[54:57]
	v_mfma_f32_16x16x32_bf16 v[46:49], v[82:85], v[190:193], v[46:49]
	v_mfma_f32_16x16x32_bf16 v[38:41], v[94:97], v[190:193], v[38:41]
	v_mfma_f32_16x16x32_bf16 v[30:33], v[82:85], v[198:201], v[30:33]
	v_mfma_f32_16x16x32_bf16 v[22:25], v[94:97], v[198:201], v[22:25]
	v_mfma_f32_16x16x32_bf16 v[14:17], v[82:85], v[206:209], v[14:17]
	v_mfma_f32_16x16x32_bf16 v[6:9], v[94:97], v[206:209], v[6:9]
	v_mfma_f32_16x16x32_bf16 v[62:65], v[86:89], v[186:189], v[62:65]
	v_mfma_f32_16x16x32_bf16 v[54:57], v[102:105], v[186:189], v[54:57]
	v_mfma_f32_16x16x32_bf16 v[46:49], v[86:89], v[194:197], v[46:49]
	v_mfma_f32_16x16x32_bf16 v[38:41], v[102:105], v[194:197], v[38:41]
	v_mfma_f32_16x16x32_bf16 v[30:33], v[86:89], v[202:205], v[30:33]
	v_mfma_f32_16x16x32_bf16 v[22:25], v[102:105], v[202:205], v[22:25]
	v_mfma_f32_16x16x32_bf16 v[14:17], v[86:89], v[210:213], v[14:17]
	v_mfma_f32_16x16x32_bf16 v[6:9], v[102:105], v[210:213], v[6:9]
	v_mfma_f32_16x16x32_bf16 v[58:61], v[134:137], v[182:185], v[58:61]
	v_mfma_f32_16x16x32_bf16 v[50:53], v[166:169], v[182:185], v[50:53]
	v_mfma_f32_16x16x32_bf16 v[42:45], v[134:137], v[190:193], v[42:45]
	v_mfma_f32_16x16x32_bf16 v[34:37], v[166:169], v[190:193], v[34:37]
	v_mfma_f32_16x16x32_bf16 v[26:29], v[134:137], v[198:201], v[26:29]
	v_mfma_f32_16x16x32_bf16 v[18:21], v[166:169], v[198:201], v[18:21]
	v_mfma_f32_16x16x32_bf16 v[10:13], v[134:137], v[206:209], v[10:13]
	v_mfma_f32_16x16x32_bf16 v[2:5], v[166:169], v[206:209], v[2:5]
	v_mfma_f32_16x16x32_bf16 v[58:61], v[162:165], v[186:189], v[58:61]
	v_mfma_f32_16x16x32_bf16 v[50:53], v[178:181], v[186:189], v[50:53]
	v_mfma_f32_16x16x32_bf16 v[42:45], v[162:165], v[194:197], v[42:45]
	v_mfma_f32_16x16x32_bf16 v[34:37], v[178:181], v[194:197], v[34:37]
	v_mfma_f32_16x16x32_bf16 v[26:29], v[162:165], v[202:205], v[26:29]
	v_mfma_f32_16x16x32_bf16 v[18:21], v[178:181], v[202:205], v[18:21]
	v_mfma_f32_16x16x32_bf16 v[10:13], v[162:165], v[210:213], v[10:13]
	v_mfma_f32_16x16x32_bf16 v[2:5], v[178:181], v[210:213], v[2:5]
	s_add_i32 s79, s79, 2
	s_add_u32 s34, s34, 0x100
	s_addc_u32 s35, s35, 0
	s_add_u32 s77, s77, 0x100
	s_addc_u32 s78, s78, 0
	s_cmp_gt_u32 s79, 13
	s_barrier
	s_cbranch_scc0 .LBB0_341
	s_and_b64 vcc, exec, s[18:19]
	s_cbranch_vccz .LBB0_344
	s_barrier

.LBB0_445:
	s_add_i32 s56, 0, 0x10000
	v_add_u32_e32 v152, s56, v145
	s_add_i32 s71, 0, 0x14000
	ds_read_b128 v[140:143], v152
	ds_read_b128 v[148:151], v152 offset:1024
	ds_read_b128 v[156:159], v152 offset:2048
	ds_read_b128 v[160:163], v152 offset:3072
	v_add_u32_e32 v152, s71, v145
	ds_read_b128 v[164:167], v152
	ds_read_b128 v[168:171], v152 offset:1024
	ds_read_b128 v[172:175], v152 offset:2048
	ds_read_b128 v[176:179], v152 offset:3072
	s_add_u32 s22, s20, 0xfffc0080
	s_addc_u32 s23, s21, -1
	s_cmp_eq_u32 s70, 12
	s_cselect_b32 s25, s13, s23
	s_cselect_b32 s24, s66, s22
	s_cselect_b32 s23, s11, s69
	s_cselect_b32 s22, s67, s68
	v_lshl_add_u64 v[152:153], s[20:21], 0, v[136:137]
	s_add_i32 m0, s19, 0xc000
	ds_read_b128 v[180:183], v147
	ds_read_b128 v[184:187], v147 offset:1024
	ds_read_b128 v[188:191], v147 offset:2048
	ds_read_b128 v[192:195], v147 offset:3072
	ds_read_b128 v[196:199], v147 offset:4096
	ds_read_b128 v[200:203], v147 offset:5120
	ds_read_b128 v[204:207], v147 offset:6144
	ds_read_b128 v[208:211], v147 offset:7168
	global_load_lds_dwordx4 v[152:153], off
	v_lshl_add_u64 v[152:153], s[20:21], 0, v[138:139]
	s_add_i32 m0, s19, 0xe000
	s_nop 0
	global_load_lds_dwordx4 v[152:153], off
	s_waitcnt vmcnt(8)
	s_waitcnt lgkmcnt(0)
	s_barrier
	s_waitcnt lgkmcnt(0)
	v_mfma_f32_16x16x32_bf16 v[126:129], v[140:143], v[180:183], v[126:129]
	v_mfma_f32_16x16x32_bf16 v[122:125], v[156:159], v[180:183], v[122:125]
	v_mfma_f32_16x16x32_bf16 v[110:113], v[140:143], v[188:191], v[110:113]
	v_mfma_f32_16x16x32_bf16 v[106:109], v[156:159], v[188:191], v[106:109]
	v_mfma_f32_16x16x32_bf16 v[94:97], v[140:143], v[196:199], v[94:97]
	v_mfma_f32_16x16x32_bf16 v[90:93], v[156:159], v[196:199], v[90:93]
	v_mfma_f32_16x16x32_bf16 v[78:81], v[140:143], v[204:207], v[78:81]
	v_mfma_f32_16x16x32_bf16 v[74:77], v[156:159], v[204:207], v[74:77]
	v_mfma_f32_16x16x32_bf16 v[126:129], v[148:151], v[184:187], v[126:129]
	v_mfma_f32_16x16x32_bf16 v[122:125], v[160:163], v[184:187], v[122:125]
	v_mfma_f32_16x16x32_bf16 v[110:113], v[148:151], v[192:195], v[110:113]
	v_mfma_f32_16x16x32_bf16 v[106:109], v[160:163], v[192:195], v[106:109]
	v_mfma_f32_16x16x32_bf16 v[94:97], v[148:151], v[200:203], v[94:97]
	v_mfma_f32_16x16x32_bf16 v[90:93], v[160:163], v[200:203], v[90:93]
	v_mfma_f32_16x16x32_bf16 v[78:81], v[148:151], v[208:211], v[78:81]
	v_mfma_f32_16x16x32_bf16 v[74:77], v[160:163], v[208:211], v[74:77]
	v_mfma_f32_16x16x32_bf16 v[118:121], v[164:167], v[180:183], v[118:121]
	v_mfma_f32_16x16x32_bf16 v[114:117], v[172:175], v[180:183], v[114:117]
	v_mfma_f32_16x16x32_bf16 v[102:105], v[164:167], v[188:191], v[102:105]
	v_mfma_f32_16x16x32_bf16 v[98:101], v[172:175], v[188:191], v[98:101]
	v_mfma_f32_16x16x32_bf16 v[86:89], v[164:167], v[196:199], v[86:89]
	v_mfma_f32_16x16x32_bf16 v[82:85], v[172:175], v[196:199], v[82:85]
	v_mfma_f32_16x16x32_bf16 v[70:73], v[164:167], v[204:207], v[70:73]
	v_mfma_f32_16x16x32_bf16 v[66:69], v[172:175], v[204:207], v[66:69]
	v_mfma_f32_16x16x32_bf16 v[118:121], v[168:171], v[184:187], v[118:121]
	v_mfma_f32_16x16x32_bf16 v[114:117], v[176:179], v[184:187], v[114:117]
	v_mfma_f32_16x16x32_bf16 v[102:105], v[168:171], v[192:195], v[102:105]
	v_mfma_f32_16x16x32_bf16 v[98:101], v[176:179], v[192:195], v[98:101]
	v_mfma_f32_16x16x32_bf16 v[86:89], v[168:171], v[200:203], v[86:89]
	v_mfma_f32_16x16x32_bf16 v[82:85], v[176:179], v[200:203], v[82:85]
	v_mfma_f32_16x16x32_bf16 v[70:73], v[168:171], v[208:211], v[70:73]
	v_mfma_f32_16x16x32_bf16 v[66:69], v[176:179], v[208:211], v[66:69]
	s_barrier
	s_add_i32 s56, s56, s35
	v_lshl_add_u64 v[152:153], s[22:23], 0, v[154:155]
	s_mov_b32 m0, s56
	ds_read_b128 v[180:183], v147 offset:16384
	ds_read_b128 v[184:187], v147 offset:17408
	ds_read_b128 v[188:191], v147 offset:18432
	ds_read_b128 v[192:195], v147 offset:19456
	ds_read_b128 v[196:199], v147 offset:20480
	ds_read_b128 v[200:203], v147 offset:21504
	ds_read_b128 v[204:207], v147 offset:22528
	ds_read_b128 v[208:211], v147 offset:23552
	global_load_lds_dwordx4 v[152:153], off
	s_add_i32 m0, s56, 0x2000
	s_add_u32 s56, s22, 0x40000
	v_lshl_add_u64 v[212:213], s[22:23], 0, v[134:135]
	s_addc_u32 s57, s23, 0
	s_add_i32 s71, s71, s35
	global_load_lds_dwordx4 v[212:213], off
	v_lshl_add_u64 v[214:215], s[56:57], 0, v[154:155]
	s_mov_b32 m0, s71
	v_lshl_add_u64 v[216:217], s[24:25], 0, v[132:133]
	global_load_lds_dwordx4 v[214:215], off
	v_lshl_add_u64 v[214:215], s[56:57], 0, v[134:135]
	s_add_i32 m0, s71, 0x2000
	s_nop 0
	global_load_lds_dwordx4 v[214:215], off
	v_lshl_add_u64 v[214:215], s[24:25], 0, v[130:131]
	s_mov_b32 m0, s19
	s_nop 0
	global_load_lds_dwordx4 v[214:215], off
	s_mov_b32 m0, s36
	s_nop 0
	global_load_lds_dwordx4 v[216:217], off
	s_waitcnt vmcnt(8)
	s_waitcnt lgkmcnt(0)
	s_barrier
	s_waitcnt lgkmcnt(0)
	v_mfma_f32_16x16x32_bf16 v[62:65], v[140:143], v[180:183], v[62:65]
	v_mfma_f32_16x16x32_bf16 v[58:61], v[156:159], v[180:183], v[58:61]
	v_mfma_f32_16x16x32_bf16 v[46:49], v[140:143], v[188:191], v[46:49]
	v_mfma_f32_16x16x32_bf16 v[42:45], v[156:159], v[188:191], v[42:45]
	v_mfma_f32_16x16x32_bf16 v[30:33], v[140:143], v[196:199], v[30:33]
	v_mfma_f32_16x16x32_bf16 v[26:29], v[156:159], v[196:199], v[26:29]
	v_mfma_f32_16x16x32_bf16 v[14:17], v[140:143], v[204:207], v[14:17]
	v_mfma_f32_16x16x32_bf16 v[10:13], v[156:159], v[204:207], v[10:13]
	v_mfma_f32_16x16x32_bf16 v[62:65], v[148:151], v[184:187], v[62:65]
	v_mfma_f32_16x16x32_bf16 v[58:61], v[160:163], v[184:187], v[58:61]
	v_mfma_f32_16x16x32_bf16 v[46:49], v[148:151], v[192:195], v[46:49]
	v_mfma_f32_16x16x32_bf16 v[42:45], v[160:163], v[192:195], v[42:45]
	v_mfma_f32_16x16x32_bf16 v[30:33], v[148:151], v[200:203], v[30:33]
	v_mfma_f32_16x16x32_bf16 v[26:29], v[160:163], v[200:203], v[26:29]
	v_mfma_f32_16x16x32_bf16 v[14:17], v[148:151], v[208:211], v[14:17]
	v_mfma_f32_16x16x32_bf16 v[10:13], v[160:163], v[208:211], v[10:13]
	v_mfma_f32_16x16x32_bf16 v[54:57], v[164:167], v[180:183], v[54:57]
	v_mfma_f32_16x16x32_bf16 v[50:53], v[172:175], v[180:183], v[50:53]
	v_mfma_f32_16x16x32_bf16 v[38:41], v[164:167], v[188:191], v[38:41]
	v_mfma_f32_16x16x32_bf16 v[34:37], v[172:175], v[188:191], v[34:37]
	v_mfma_f32_16x16x32_bf16 v[22:25], v[164:167], v[196:199], v[22:25]
	v_mfma_f32_16x16x32_bf16 v[18:21], v[172:175], v[196:199], v[18:21]
	v_mfma_f32_16x16x32_bf16 v[6:9], v[164:167], v[204:207], v[6:9]
	v_mfma_f32_16x16x32_bf16 v[2:5], v[172:175], v[204:207], v[2:5]
	v_mfma_f32_16x16x32_bf16 v[54:57], v[168:171], v[184:187], v[54:57]
	v_mfma_f32_16x16x32_bf16 v[50:53], v[176:179], v[184:187], v[50:53]
	v_mfma_f32_16x16x32_bf16 v[38:41], v[168:171], v[192:195], v[38:41]
	v_mfma_f32_16x16x32_bf16 v[34:37], v[176:179], v[192:195], v[34:37]
	v_mfma_f32_16x16x32_bf16 v[22:25], v[168:171], v[200:203], v[22:25]
	v_mfma_f32_16x16x32_bf16 v[18:21], v[176:179], v[200:203], v[18:21]
	v_mfma_f32_16x16x32_bf16 v[6:9], v[168:171], v[208:211], v[6:9]
	v_mfma_f32_16x16x32_bf16 v[2:5], v[176:179], v[208:211], v[2:5]
	s_barrier
	s_add_i32 s56, 0, 0x18000
	s_add_i32 s57, 0, 0x1c000
	v_add_u32_e32 v160, s56, v145
	v_add_u32_e32 v176, s57, v145
	ds_read_b128 v[140:143], v160
	ds_read_b128 v[148:151], v160 offset:1024
	ds_read_b128 v[156:159], v160 offset:2048
	ds_read_b128 v[160:163], v160 offset:3072
	ds_read_b128 v[164:167], v176
	ds_read_b128 v[168:171], v176 offset:1024
	ds_read_b128 v[172:175], v176 offset:2048
	ds_read_b128 v[176:179], v176 offset:3072
	s_add_u32 s24, s24, 0x40000
	s_addc_u32 s25, s25, 0
	s_mov_b32 m0, s37
	v_lshl_add_u64 v[218:219], s[24:25], 0, v[130:131]
	ds_read_b128 v[180:183], v147 offset:32768
	ds_read_b128 v[184:187], v147 offset:33792
	ds_read_b128 v[188:191], v147 offset:34816
	ds_read_b128 v[192:195], v147 offset:35840
	ds_read_b128 v[196:199], v147 offset:36864
	ds_read_b128 v[200:203], v147 offset:37888
	ds_read_b128 v[204:207], v147 offset:38912
	ds_read_b128 v[208:211], v147 offset:39936
	global_load_lds_dwordx4 v[218:219], off
	v_lshl_add_u64 v[218:219], s[24:25], 0, v[132:133]
	s_mov_b32 m0, s38
	s_nop 0
	global_load_lds_dwordx4 v[218:219], off
	s_waitcnt vmcnt(8)
	s_waitcnt lgkmcnt(0)
	s_barrier
	s_waitcnt lgkmcnt(0)
	v_mfma_f32_16x16x32_bf16 v[126:129], v[140:143], v[180:183], v[126:129]
	v_mfma_f32_16x16x32_bf16 v[122:125], v[156:159], v[180:183], v[122:125]
	v_mfma_f32_16x16x32_bf16 v[110:113], v[140:143], v[188:191], v[110:113]
	v_mfma_f32_16x16x32_bf16 v[106:109], v[156:159], v[188:191], v[106:109]
	v_mfma_f32_16x16x32_bf16 v[94:97], v[140:143], v[196:199], v[94:97]
	v_mfma_f32_16x16x32_bf16 v[90:93], v[156:159], v[196:199], v[90:93]
	v_mfma_f32_16x16x32_bf16 v[78:81], v[140:143], v[204:207], v[78:81]
	v_mfma_f32_16x16x32_bf16 v[74:77], v[156:159], v[204:207], v[74:77]
	v_mfma_f32_16x16x32_bf16 v[126:129], v[148:151], v[184:187], v[126:129]
	v_mfma_f32_16x16x32_bf16 v[122:125], v[160:163], v[184:187], v[122:125]
	v_mfma_f32_16x16x32_bf16 v[110:113], v[148:151], v[192:195], v[110:113]
	v_mfma_f32_16x16x32_bf16 v[106:109], v[160:163], v[192:195], v[106:109]
	v_mfma_f32_16x16x32_bf16 v[94:97], v[148:151], v[200:203], v[94:97]
	v_mfma_f32_16x16x32_bf16 v[90:93], v[160:163], v[200:203], v[90:93]
	v_mfma_f32_16x16x32_bf16 v[78:81], v[148:151], v[208:211], v[78:81]
	v_mfma_f32_16x16x32_bf16 v[74:77], v[160:163], v[208:211], v[74:77]
	v_mfma_f32_16x16x32_bf16 v[118:121], v[164:167], v[180:183], v[118:121]
	v_mfma_f32_16x16x32_bf16 v[114:117], v[172:175], v[180:183], v[114:117]
	v_mfma_f32_16x16x32_bf16 v[102:105], v[164:167], v[188:191], v[102:105]
	v_mfma_f32_16x16x32_bf16 v[98:101], v[172:175], v[188:191], v[98:101]
	v_mfma_f32_16x16x32_bf16 v[86:89], v[164:167], v[196:199], v[86:89]
	v_mfma_f32_16x16x32_bf16 v[82:85], v[172:175], v[196:199], v[82:85]
	v_mfma_f32_16x16x32_bf16 v[70:73], v[164:167], v[204:207], v[70:73]
	v_mfma_f32_16x16x32_bf16 v[66:69], v[172:175], v[204:207], v[66:69]
	v_mfma_f32_16x16x32_bf16 v[118:121], v[168:171], v[184:187], v[118:121]
	v_mfma_f32_16x16x32_bf16 v[114:117], v[176:179], v[184:187], v[114:117]
	v_mfma_f32_16x16x32_bf16 v[102:105], v[168:171], v[192:195], v[102:105]
	v_mfma_f32_16x16x32_bf16 v[98:101], v[176:179], v[192:195], v[98:101]
	v_mfma_f32_16x16x32_bf16 v[86:89], v[168:171], v[200:203], v[86:89]
	v_mfma_f32_16x16x32_bf16 v[82:85], v[176:179], v[200:203], v[82:85]
	v_mfma_f32_16x16x32_bf16 v[70:73], v[168:171], v[208:211], v[70:73]
	v_mfma_f32_16x16x32_bf16 v[66:69], v[176:179], v[208:211], v[66:69]
	s_barrier
	s_add_i32 s24, s56, s35
	v_lshl_add_u64 v[152:153], v[152:153], 0, s[62:63]
	s_mov_b32 m0, s24
	ds_read_b128 v[180:183], v147 offset:49152
	ds_read_b128 v[184:187], v147 offset:50176
	ds_read_b128 v[188:191], v147 offset:51200
	ds_read_b128 v[192:195], v147 offset:52224
	ds_read_b128 v[196:199], v147 offset:53248
	ds_read_b128 v[200:203], v147 offset:54272
	ds_read_b128 v[204:207], v147 offset:55296
	ds_read_b128 v[208:211], v147 offset:56320
	global_load_lds_dwordx4 v[152:153], off
	s_add_i32 m0, s24, 0x2000
	s_add_u32 s22, s22, 0x40080
	v_lshl_add_u64 v[152:153], v[212:213], 0, s[62:63]
	s_addc_u32 s23, s23, 0
	s_add_i32 s24, s57, s35
	global_load_lds_dwordx4 v[152:153], off
	v_lshl_add_u64 v[152:153], s[22:23], 0, v[154:155]
	s_mov_b32 m0, s24
	s_nop 0
	global_load_lds_dwordx4 v[152:153], off
	v_lshl_add_u64 v[152:153], s[22:23], 0, v[134:135]
	s_add_i32 m0, s24, 0x2000
	s_nop 0
	global_load_lds_dwordx4 v[152:153], off
	v_lshl_add_u64 v[152:153], v[214:215], 0, s[62:63]
	s_mov_b32 m0, s39
	s_nop 0
	global_load_lds_dwordx4 v[152:153], off
	v_lshl_add_u64 v[152:153], v[216:217], 0, s[62:63]
	s_mov_b32 m0, s40
	s_nop 0
	global_load_lds_dwordx4 v[152:153], off
	s_waitcnt vmcnt(8)
	s_waitcnt lgkmcnt(0)
	s_barrier
	s_waitcnt lgkmcnt(0)
	v_mfma_f32_16x16x32_bf16 v[62:65], v[140:143], v[180:183], v[62:65]
	v_mfma_f32_16x16x32_bf16 v[58:61], v[156:159], v[180:183], v[58:61]
	v_mfma_f32_16x16x32_bf16 v[46:49], v[140:143], v[188:191], v[46:49]
	v_mfma_f32_16x16x32_bf16 v[42:45], v[156:159], v[188:191], v[42:45]
	v_mfma_f32_16x16x32_bf16 v[30:33], v[140:143], v[196:199], v[30:33]
	v_mfma_f32_16x16x32_bf16 v[26:29], v[156:159], v[196:199], v[26:29]
	v_mfma_f32_16x16x32_bf16 v[14:17], v[140:143], v[204:207], v[14:17]
	v_mfma_f32_16x16x32_bf16 v[10:13], v[156:159], v[204:207], v[10:13]
	v_mfma_f32_16x16x32_bf16 v[62:65], v[148:151], v[184:187], v[62:65]
	v_mfma_f32_16x16x32_bf16 v[58:61], v[160:163], v[184:187], v[58:61]
	v_mfma_f32_16x16x32_bf16 v[46:49], v[148:151], v[192:195], v[46:49]
	v_mfma_f32_16x16x32_bf16 v[42:45], v[160:163], v[192:195], v[42:45]
	v_mfma_f32_16x16x32_bf16 v[30:33], v[148:151], v[200:203], v[30:33]
	v_mfma_f32_16x16x32_bf16 v[26:29], v[160:163], v[200:203], v[26:29]
	v_mfma_f32_16x16x32_bf16 v[14:17], v[148:151], v[208:211], v[14:17]
	v_mfma_f32_16x16x32_bf16 v[10:13], v[160:163], v[208:211], v[10:13]
	v_mfma_f32_16x16x32_bf16 v[54:57], v[164:167], v[180:183], v[54:57]
	v_mfma_f32_16x16x32_bf16 v[50:53], v[172:175], v[180:183], v[50:53]
	v_mfma_f32_16x16x32_bf16 v[38:41], v[164:167], v[188:191], v[38:41]
	v_mfma_f32_16x16x32_bf16 v[34:37], v[172:175], v[188:191], v[34:37]
	v_mfma_f32_16x16x32_bf16 v[22:25], v[164:167], v[196:199], v[22:25]
	v_mfma_f32_16x16x32_bf16 v[18:21], v[172:175], v[196:199], v[18:21]
	v_mfma_f32_16x16x32_bf16 v[6:9], v[164:167], v[204:207], v[6:9]
	v_mfma_f32_16x16x32_bf16 v[2:5], v[172:175], v[204:207], v[2:5]
	v_mfma_f32_16x16x32_bf16 v[54:57], v[168:171], v[184:187], v[54:57]
	v_mfma_f32_16x16x32_bf16 v[50:53], v[176:179], v[184:187], v[50:53]
	v_mfma_f32_16x16x32_bf16 v[38:41], v[168:171], v[192:195], v[38:41]
	v_mfma_f32_16x16x32_bf16 v[34:37], v[176:179], v[192:195], v[34:37]
	v_mfma_f32_16x16x32_bf16 v[22:25], v[168:171], v[200:203], v[22:25]
	v_mfma_f32_16x16x32_bf16 v[18:21], v[176:179], v[200:203], v[18:21]
	v_mfma_f32_16x16x32_bf16 v[6:9], v[168:171], v[208:211], v[6:9]
	v_mfma_f32_16x16x32_bf16 v[2:5], v[176:179], v[208:211], v[2:5]
	s_add_i32 s70, s70, 2
	s_add_u32 s20, s20, 0x100
	s_addc_u32 s21, s21, 0
	s_add_u32 s68, s68, 0x100
	s_addc_u32 s69, s69, 0
	s_cmp_gt_u32 s70, 13
	s_barrier
	s_cbranch_scc0 .LBB0_445
	s_and_b64 vcc, exec, s[8:9]
	s_cbranch_vccz .LBB0_448
	s_barrier

.LBB0_534:
	s_add_i32 s56, 0, 0x10000
	v_add_u32_e32 v152, s56, v159
	s_add_i32 s70, 0, 0x14000
	ds_read_b128 v[130:133], v152
	ds_read_b128 v[134:137], v152 offset:1024
	ds_read_b128 v[148:151], v152 offset:2048
	ds_read_b128 v[162:165], v152 offset:3072
	v_add_u32_e32 v152, s70, v159
	ds_read_b128 v[166:169], v152
	ds_read_b128 v[170:173], v152 offset:1024
	ds_read_b128 v[174:177], v152 offset:2048
	ds_read_b128 v[178:181], v152 offset:3072
	s_add_u32 s24, s22, 0xfff00080
	s_addc_u32 s25, s23, -1
	s_cmp_eq_u32 s69, 60
	s_cselect_b32 s27, s13, s25
	s_cselect_b32 s26, s19, s24
	s_cselect_b32 s25, s11, s68
	s_cselect_b32 s24, s21, s40
	v_lshl_add_u64 v[152:153], s[22:23], 0, v[144:145]
	s_add_i32 m0, s38, 0xc000
	ds_read_b128 v[182:185], v161
	ds_read_b128 v[186:189], v161 offset:1024
	ds_read_b128 v[190:193], v161 offset:2048
	ds_read_b128 v[194:197], v161 offset:3072
	ds_read_b128 v[198:201], v161 offset:4096
	ds_read_b128 v[202:205], v161 offset:5120
	ds_read_b128 v[206:209], v161 offset:6144
	ds_read_b128 v[210:213], v161 offset:7168
	global_load_lds_dwordx4 v[152:153], off
	v_lshl_add_u64 v[152:153], s[22:23], 0, v[146:147]
	s_add_i32 m0, s38, 0xe000
	s_nop 0
	global_load_lds_dwordx4 v[152:153], off
	s_waitcnt vmcnt(8)
	s_waitcnt lgkmcnt(0)
	s_barrier
	s_waitcnt lgkmcnt(0)
	v_mfma_f32_16x16x32_bf16 v[126:129], v[130:133], v[182:185], v[126:129]
	v_mfma_f32_16x16x32_bf16 v[122:125], v[148:151], v[182:185], v[122:125]
	v_mfma_f32_16x16x32_bf16 v[110:113], v[130:133], v[190:193], v[110:113]
	v_mfma_f32_16x16x32_bf16 v[106:109], v[148:151], v[190:193], v[106:109]
	v_mfma_f32_16x16x32_bf16 v[94:97], v[130:133], v[198:201], v[94:97]
	v_mfma_f32_16x16x32_bf16 v[90:93], v[148:151], v[198:201], v[90:93]
	v_mfma_f32_16x16x32_bf16 v[78:81], v[130:133], v[206:209], v[78:81]
	v_mfma_f32_16x16x32_bf16 v[74:77], v[148:151], v[206:209], v[74:77]
	v_mfma_f32_16x16x32_bf16 v[126:129], v[134:137], v[186:189], v[126:129]
	v_mfma_f32_16x16x32_bf16 v[122:125], v[162:165], v[186:189], v[122:125]
	v_mfma_f32_16x16x32_bf16 v[110:113], v[134:137], v[194:197], v[110:113]
	v_mfma_f32_16x16x32_bf16 v[106:109], v[162:165], v[194:197], v[106:109]
	v_mfma_f32_16x16x32_bf16 v[94:97], v[134:137], v[202:205], v[94:97]
	v_mfma_f32_16x16x32_bf16 v[90:93], v[162:165], v[202:205], v[90:93]
	v_mfma_f32_16x16x32_bf16 v[78:81], v[134:137], v[210:213], v[78:81]
	v_mfma_f32_16x16x32_bf16 v[74:77], v[162:165], v[210:213], v[74:77]
	v_mfma_f32_16x16x32_bf16 v[118:121], v[166:169], v[182:185], v[118:121]
	v_mfma_f32_16x16x32_bf16 v[114:117], v[174:177], v[182:185], v[114:117]
	v_mfma_f32_16x16x32_bf16 v[102:105], v[166:169], v[190:193], v[102:105]
	v_mfma_f32_16x16x32_bf16 v[98:101], v[174:177], v[190:193], v[98:101]
	v_mfma_f32_16x16x32_bf16 v[86:89], v[166:169], v[198:201], v[86:89]
	v_mfma_f32_16x16x32_bf16 v[82:85], v[174:177], v[198:201], v[82:85]
	v_mfma_f32_16x16x32_bf16 v[70:73], v[166:169], v[206:209], v[70:73]
	v_mfma_f32_16x16x32_bf16 v[66:69], v[174:177], v[206:209], v[66:69]
	v_mfma_f32_16x16x32_bf16 v[118:121], v[170:173], v[186:189], v[118:121]
	v_mfma_f32_16x16x32_bf16 v[114:117], v[178:181], v[186:189], v[114:117]
	v_mfma_f32_16x16x32_bf16 v[102:105], v[170:173], v[194:197], v[102:105]
	v_mfma_f32_16x16x32_bf16 v[98:101], v[178:181], v[194:197], v[98:101]
	v_mfma_f32_16x16x32_bf16 v[86:89], v[170:173], v[202:205], v[86:89]
	v_mfma_f32_16x16x32_bf16 v[82:85], v[178:181], v[202:205], v[82:85]
	v_mfma_f32_16x16x32_bf16 v[70:73], v[170:173], v[210:213], v[70:73]
	v_mfma_f32_16x16x32_bf16 v[66:69], v[178:181], v[210:213], v[66:69]
	s_barrier
	s_add_i32 s56, s56, s37
	v_lshl_add_u64 v[152:153], s[24:25], 0, v[154:155]
	s_mov_b32 m0, s56
	ds_read_b128 v[182:185], v161 offset:16384
	ds_read_b128 v[186:189], v161 offset:17408
	ds_read_b128 v[190:193], v161 offset:18432
	ds_read_b128 v[194:197], v161 offset:19456
	ds_read_b128 v[198:201], v161 offset:20480
	ds_read_b128 v[202:205], v161 offset:21504
	ds_read_b128 v[206:209], v161 offset:22528
	ds_read_b128 v[210:213], v161 offset:23552
	global_load_lds_dwordx4 v[152:153], off
	s_add_i32 m0, s56, 0x2000
	s_add_u32 s56, s24, 0x100000
	v_lshl_add_u64 v[156:157], s[24:25], 0, v[142:143]
	s_addc_u32 s57, s25, 0
	s_add_i32 s70, s70, s37
	global_load_lds_dwordx4 v[156:157], off
	v_lshl_add_u64 v[214:215], s[56:57], 0, v[154:155]
	s_mov_b32 m0, s70
	v_lshl_add_u64 v[216:217], s[26:27], 0, v[140:141]
	global_load_lds_dwordx4 v[214:215], off
	v_lshl_add_u64 v[214:215], s[56:57], 0, v[142:143]
	s_add_i32 m0, s70, 0x2000
	s_nop 0
	global_load_lds_dwordx4 v[214:215], off
	v_lshl_add_u64 v[214:215], s[26:27], 0, v[138:139]
	s_mov_b32 m0, s38
	s_nop 0
	global_load_lds_dwordx4 v[214:215], off
	s_mov_b32 m0, s39
	s_nop 0
	global_load_lds_dwordx4 v[216:217], off
	s_waitcnt vmcnt(8)
	s_waitcnt lgkmcnt(0)
	s_barrier
	s_waitcnt lgkmcnt(0)
	v_mfma_f32_16x16x32_bf16 v[62:65], v[130:133], v[182:185], v[62:65]
	v_mfma_f32_16x16x32_bf16 v[58:61], v[148:151], v[182:185], v[58:61]
	v_mfma_f32_16x16x32_bf16 v[46:49], v[130:133], v[190:193], v[46:49]
	v_mfma_f32_16x16x32_bf16 v[42:45], v[148:151], v[190:193], v[42:45]
	v_mfma_f32_16x16x32_bf16 v[30:33], v[130:133], v[198:201], v[30:33]
	v_mfma_f32_16x16x32_bf16 v[26:29], v[148:151], v[198:201], v[26:29]
	v_mfma_f32_16x16x32_bf16 v[14:17], v[130:133], v[206:209], v[14:17]
	v_mfma_f32_16x16x32_bf16 v[10:13], v[148:151], v[206:209], v[10:13]
	v_mfma_f32_16x16x32_bf16 v[62:65], v[134:137], v[186:189], v[62:65]
	v_mfma_f32_16x16x32_bf16 v[58:61], v[162:165], v[186:189], v[58:61]
	v_mfma_f32_16x16x32_bf16 v[46:49], v[134:137], v[194:197], v[46:49]
	v_mfma_f32_16x16x32_bf16 v[42:45], v[162:165], v[194:197], v[42:45]
	v_mfma_f32_16x16x32_bf16 v[30:33], v[134:137], v[202:205], v[30:33]
	v_mfma_f32_16x16x32_bf16 v[26:29], v[162:165], v[202:205], v[26:29]
	v_mfma_f32_16x16x32_bf16 v[14:17], v[134:137], v[210:213], v[14:17]
	v_mfma_f32_16x16x32_bf16 v[10:13], v[162:165], v[210:213], v[10:13]
	v_mfma_f32_16x16x32_bf16 v[54:57], v[166:169], v[182:185], v[54:57]
	v_mfma_f32_16x16x32_bf16 v[50:53], v[174:177], v[182:185], v[50:53]
	v_mfma_f32_16x16x32_bf16 v[38:41], v[166:169], v[190:193], v[38:41]
	v_mfma_f32_16x16x32_bf16 v[34:37], v[174:177], v[190:193], v[34:37]
	v_mfma_f32_16x16x32_bf16 v[22:25], v[166:169], v[198:201], v[22:25]
	v_mfma_f32_16x16x32_bf16 v[18:21], v[174:177], v[198:201], v[18:21]
	v_mfma_f32_16x16x32_bf16 v[6:9], v[166:169], v[206:209], v[6:9]
	v_mfma_f32_16x16x32_bf16 v[2:5], v[174:177], v[206:209], v[2:5]
	v_mfma_f32_16x16x32_bf16 v[54:57], v[170:173], v[186:189], v[54:57]
	v_mfma_f32_16x16x32_bf16 v[50:53], v[178:181], v[186:189], v[50:53]
	v_mfma_f32_16x16x32_bf16 v[38:41], v[170:173], v[194:197], v[38:41]
	v_mfma_f32_16x16x32_bf16 v[34:37], v[178:181], v[194:197], v[34:37]
	v_mfma_f32_16x16x32_bf16 v[22:25], v[170:173], v[202:205], v[22:25]
	v_mfma_f32_16x16x32_bf16 v[18:21], v[178:181], v[202:205], v[18:21]
	v_mfma_f32_16x16x32_bf16 v[6:9], v[170:173], v[210:213], v[6:9]
	v_mfma_f32_16x16x32_bf16 v[2:5], v[178:181], v[210:213], v[2:5]
	s_barrier
	s_add_i32 s56, 0, 0x18000
	s_add_i32 s57, 0, 0x1c000
	v_add_u32_e32 v162, s56, v159
	v_add_u32_e32 v178, s57, v159
	ds_read_b128 v[130:133], v162
	ds_read_b128 v[134:137], v162 offset:1024
	ds_read_b128 v[148:151], v162 offset:2048
	ds_read_b128 v[162:165], v162 offset:3072
	ds_read_b128 v[166:169], v178
	ds_read_b128 v[170:173], v178 offset:1024
	ds_read_b128 v[174:177], v178 offset:2048
	ds_read_b128 v[178:181], v178 offset:3072
	s_add_u32 s26, s26, 0x100000
	s_addc_u32 s27, s27, 0
	s_mov_b32 m0, s44
	v_lshl_add_u64 v[218:219], s[26:27], 0, v[138:139]
	ds_read_b128 v[182:185], v161 offset:32768
	ds_read_b128 v[186:189], v161 offset:33792
	ds_read_b128 v[190:193], v161 offset:34816
	ds_read_b128 v[194:197], v161 offset:35840
	ds_read_b128 v[198:201], v161 offset:36864
	ds_read_b128 v[202:205], v161 offset:37888
	ds_read_b128 v[206:209], v161 offset:38912
	ds_read_b128 v[210:213], v161 offset:39936
	global_load_lds_dwordx4 v[218:219], off
	v_lshl_add_u64 v[218:219], s[26:27], 0, v[140:141]
	s_mov_b32 m0, s45
	s_nop 0
	global_load_lds_dwordx4 v[218:219], off
	s_waitcnt vmcnt(8)
	s_waitcnt lgkmcnt(0)
	s_barrier
	s_waitcnt lgkmcnt(0)
	v_mfma_f32_16x16x32_bf16 v[126:129], v[130:133], v[182:185], v[126:129]
	v_mfma_f32_16x16x32_bf16 v[122:125], v[148:151], v[182:185], v[122:125]
	v_mfma_f32_16x16x32_bf16 v[110:113], v[130:133], v[190:193], v[110:113]
	v_mfma_f32_16x16x32_bf16 v[106:109], v[148:151], v[190:193], v[106:109]
	v_mfma_f32_16x16x32_bf16 v[94:97], v[130:133], v[198:201], v[94:97]
	v_mfma_f32_16x16x32_bf16 v[90:93], v[148:151], v[198:201], v[90:93]
	v_mfma_f32_16x16x32_bf16 v[78:81], v[130:133], v[206:209], v[78:81]
	v_mfma_f32_16x16x32_bf16 v[74:77], v[148:151], v[206:209], v[74:77]
	v_mfma_f32_16x16x32_bf16 v[126:129], v[134:137], v[186:189], v[126:129]
	v_mfma_f32_16x16x32_bf16 v[122:125], v[162:165], v[186:189], v[122:125]
	v_mfma_f32_16x16x32_bf16 v[110:113], v[134:137], v[194:197], v[110:113]
	v_mfma_f32_16x16x32_bf16 v[106:109], v[162:165], v[194:197], v[106:109]
	v_mfma_f32_16x16x32_bf16 v[94:97], v[134:137], v[202:205], v[94:97]
	v_mfma_f32_16x16x32_bf16 v[90:93], v[162:165], v[202:205], v[90:93]
	v_mfma_f32_16x16x32_bf16 v[78:81], v[134:137], v[210:213], v[78:81]
	v_mfma_f32_16x16x32_bf16 v[74:77], v[162:165], v[210:213], v[74:77]
	v_mfma_f32_16x16x32_bf16 v[118:121], v[166:169], v[182:185], v[118:121]
	v_mfma_f32_16x16x32_bf16 v[114:117], v[174:177], v[182:185], v[114:117]
	v_mfma_f32_16x16x32_bf16 v[102:105], v[166:169], v[190:193], v[102:105]
	v_mfma_f32_16x16x32_bf16 v[98:101], v[174:177], v[190:193], v[98:101]
	v_mfma_f32_16x16x32_bf16 v[86:89], v[166:169], v[198:201], v[86:89]
	v_mfma_f32_16x16x32_bf16 v[82:85], v[174:177], v[198:201], v[82:85]
	v_mfma_f32_16x16x32_bf16 v[70:73], v[166:169], v[206:209], v[70:73]
	v_mfma_f32_16x16x32_bf16 v[66:69], v[174:177], v[206:209], v[66:69]
	v_mfma_f32_16x16x32_bf16 v[118:121], v[170:173], v[186:189], v[118:121]
	v_mfma_f32_16x16x32_bf16 v[114:117], v[178:181], v[186:189], v[114:117]
	v_mfma_f32_16x16x32_bf16 v[102:105], v[170:173], v[194:197], v[102:105]
	v_mfma_f32_16x16x32_bf16 v[98:101], v[178:181], v[194:197], v[98:101]
	v_mfma_f32_16x16x32_bf16 v[86:89], v[170:173], v[202:205], v[86:89]
	v_mfma_f32_16x16x32_bf16 v[82:85], v[178:181], v[202:205], v[82:85]
	v_mfma_f32_16x16x32_bf16 v[70:73], v[170:173], v[210:213], v[70:73]
	v_mfma_f32_16x16x32_bf16 v[66:69], v[178:181], v[210:213], v[66:69]
	s_barrier
	s_add_i32 s26, s56, s37
	v_lshl_add_u64 v[152:153], v[152:153], 0, s[62:63]
	s_mov_b32 m0, s26
	ds_read_b128 v[182:185], v161 offset:49152
	ds_read_b128 v[186:189], v161 offset:50176
	ds_read_b128 v[190:193], v161 offset:51200
	ds_read_b128 v[194:197], v161 offset:52224
	ds_read_b128 v[198:201], v161 offset:53248
	ds_read_b128 v[202:205], v161 offset:54272
	ds_read_b128 v[206:209], v161 offset:55296
	ds_read_b128 v[210:213], v161 offset:56320
	global_load_lds_dwordx4 v[152:153], off
	s_add_i32 m0, s26, 0x2000
	s_add_u32 s24, s24, 0x100080
	v_lshl_add_u64 v[152:153], v[156:157], 0, s[62:63]
	s_addc_u32 s25, s25, 0
	s_add_i32 s26, s57, s37
	global_load_lds_dwordx4 v[152:153], off
	v_lshl_add_u64 v[152:153], s[24:25], 0, v[154:155]
	s_mov_b32 m0, s26
	s_nop 0
	global_load_lds_dwordx4 v[152:153], off
	v_lshl_add_u64 v[152:153], s[24:25], 0, v[142:143]
	s_add_i32 m0, s26, 0x2000
	s_nop 0
	global_load_lds_dwordx4 v[152:153], off
	v_lshl_add_u64 v[152:153], v[214:215], 0, s[62:63]
	s_mov_b32 m0, s53
	s_nop 0
	global_load_lds_dwordx4 v[152:153], off
	v_lshl_add_u64 v[152:153], v[216:217], 0, s[62:63]
	s_mov_b32 m0, s55
	s_nop 0
	global_load_lds_dwordx4 v[152:153], off
	s_waitcnt vmcnt(8)
	s_waitcnt lgkmcnt(0)
	s_barrier
	s_waitcnt lgkmcnt(0)
	v_mfma_f32_16x16x32_bf16 v[62:65], v[130:133], v[182:185], v[62:65]
	v_mfma_f32_16x16x32_bf16 v[58:61], v[148:151], v[182:185], v[58:61]
	v_mfma_f32_16x16x32_bf16 v[46:49], v[130:133], v[190:193], v[46:49]
	v_mfma_f32_16x16x32_bf16 v[42:45], v[148:151], v[190:193], v[42:45]
	v_mfma_f32_16x16x32_bf16 v[30:33], v[130:133], v[198:201], v[30:33]
	v_mfma_f32_16x16x32_bf16 v[26:29], v[148:151], v[198:201], v[26:29]
	v_mfma_f32_16x16x32_bf16 v[14:17], v[130:133], v[206:209], v[14:17]
	v_mfma_f32_16x16x32_bf16 v[10:13], v[148:151], v[206:209], v[10:13]
	v_mfma_f32_16x16x32_bf16 v[62:65], v[134:137], v[186:189], v[62:65]
	v_mfma_f32_16x16x32_bf16 v[58:61], v[162:165], v[186:189], v[58:61]
	v_mfma_f32_16x16x32_bf16 v[46:49], v[134:137], v[194:197], v[46:49]
	v_mfma_f32_16x16x32_bf16 v[42:45], v[162:165], v[194:197], v[42:45]
	v_mfma_f32_16x16x32_bf16 v[30:33], v[134:137], v[202:205], v[30:33]
	v_mfma_f32_16x16x32_bf16 v[26:29], v[162:165], v[202:205], v[26:29]
	v_mfma_f32_16x16x32_bf16 v[14:17], v[134:137], v[210:213], v[14:17]
	v_mfma_f32_16x16x32_bf16 v[10:13], v[162:165], v[210:213], v[10:13]
	v_mfma_f32_16x16x32_bf16 v[54:57], v[166:169], v[182:185], v[54:57]
	v_mfma_f32_16x16x32_bf16 v[50:53], v[174:177], v[182:185], v[50:53]
	v_mfma_f32_16x16x32_bf16 v[38:41], v[166:169], v[190:193], v[38:41]
	v_mfma_f32_16x16x32_bf16 v[34:37], v[174:177], v[190:193], v[34:37]
	v_mfma_f32_16x16x32_bf16 v[22:25], v[166:169], v[198:201], v[22:25]
	v_mfma_f32_16x16x32_bf16 v[18:21], v[174:177], v[198:201], v[18:21]
	v_mfma_f32_16x16x32_bf16 v[6:9], v[166:169], v[206:209], v[6:9]
	v_mfma_f32_16x16x32_bf16 v[2:5], v[174:177], v[206:209], v[2:5]
	v_mfma_f32_16x16x32_bf16 v[54:57], v[170:173], v[186:189], v[54:57]
	v_mfma_f32_16x16x32_bf16 v[50:53], v[178:181], v[186:189], v[50:53]
	v_mfma_f32_16x16x32_bf16 v[38:41], v[170:173], v[194:197], v[38:41]
	v_mfma_f32_16x16x32_bf16 v[34:37], v[178:181], v[194:197], v[34:37]
	v_mfma_f32_16x16x32_bf16 v[22:25], v[170:173], v[202:205], v[22:25]
	v_mfma_f32_16x16x32_bf16 v[18:21], v[178:181], v[202:205], v[18:21]
	v_mfma_f32_16x16x32_bf16 v[6:9], v[170:173], v[210:213], v[6:9]
	v_mfma_f32_16x16x32_bf16 v[2:5], v[178:181], v[210:213], v[2:5]
	s_add_i32 s69, s69, 2
	s_add_u32 s22, s22, 0x100
	s_addc_u32 s23, s23, 0
	s_add_u32 s40, s40, 0x100
	s_addc_u32 s68, s68, 0
	s_cmp_gt_u32 s69, 61
	s_barrier
	s_cbranch_scc0 .LBB0_534
	v_lshl_add_u32 v148, s20, 8, v158
	v_lshl_or_b32 v150, s18, 8, v160
	v_ashrrev_i32_e32 v149, 31, v148
	v_lshlrev_b64 v[130:131], 11, v[148:149]
	v_ashrrev_i32_e32 v151, 31, v150
	v_lshl_add_u64 v[130:131], s[8:9], 0, v[130:131]
	v_lshlrev_b64 v[132:133], 1, v[150:151]
	v_lshl_add_u64 v[172:173], v[130:131], 0, v[132:133]
	global_load_dwordx4 v[164:167], v[172:173], off
	global_load_dwordx4 v[168:171], v[172:173], off offset:256
	v_or_b32_e32 v152, 16, v148
	v_ashrrev_i32_e32 v153, 31, v152
	v_lshlrev_b64 v[130:131], 11, v[152:153]
	v_lshl_add_u64 v[130:131], s[8:9], 0, v[130:131]
	v_lshl_add_u64 v[156:157], v[130:131], 0, v[132:133]
	global_load_dwordx4 v[134:137], v[156:157], off
	global_load_dwordx4 v[130:133], v[156:157], off offset:256
	v_and_b32_e32 v163, 64, v1
	v_xor_b32_e32 v162, 16, v1
	v_add_u32_e32 v163, 64, v163
	v_xor_b32_e32 v174, 32, v1
	v_cmp_lt_i32_e32 vcc, v162, v163
	s_lshl_b32 s18, s18, 2
	s_ashr_i32 s19, s18, 31
	v_cndmask_b32_e32 v162, v1, v162, vcc
	v_cmp_lt_i32_e32 vcc, v174, v163
	v_lshlrev_b32_e32 v162, 2, v162
	s_waitcnt vmcnt(0)
	v_and_b32_e32 v175, 0xffff0000, v164
	v_cndmask_b32_e32 v163, v1, v174, vcc
	v_lshlrev_b32_e32 v174, 16, v164
	v_lshlrev_b32_e32 v164, 16, v165
	v_and_b32_e32 v165, 0xffff0000, v165
	v_lshlrev_b32_e32 v176, 16, v166
	v_and_b32_e32 v177, 0xffff0000, v166
	v_lshlrev_b32_e32 v166, 16, v167
	v_and_b32_e32 v167, 0xffff0000, v167
	v_lshlrev_b32_e32 v178, 16, v168
	v_and_b32_e32 v179, 0xffff0000, v168
	v_lshlrev_b32_e32 v168, 16, v169
	v_and_b32_e32 v169, 0xffff0000, v169
	v_lshlrev_b32_e32 v180, 16, v170
	v_and_b32_e32 v181, 0xffff0000, v170
	v_lshlrev_b32_e32 v170, 16, v171
	v_and_b32_e32 v171, 0xffff0000, v171
	v_pk_add_f32 v[128:129], v[128:129], v[164:165]
	v_pk_add_f32 v[126:127], v[126:127], v[174:175]
	v_pk_add_f32 v[122:123], v[122:123], v[176:177]
	v_pk_add_f32 v[124:125], v[124:125], v[166:167]
	v_pk_add_f32 v[120:121], v[120:121], v[168:169]
	v_pk_add_f32 v[118:119], v[118:119], v[178:179]
	v_pk_add_f32 v[164:165], v[114:115], v[180:181]
	v_pk_add_f32 v[166:167], v[116:117], v[170:171]
	v_cvt_pk_bf16_f32 v114, v126, v127
	v_cvt_pk_bf16_f32 v115, v128, v129
	v_mul_f32_e32 v116, v126, v126
	v_mul_f32_e32 v117, v128, v128
	v_mul_f32_e32 v126, v122, v122
	v_mul_f32_e32 v128, v125, v125
	v_mul_f32_e32 v168, v118, v118
	v_mul_f32_e32 v169, v120, v120
	v_mul_f32_e32 v170, v164, v164
	v_mul_f32_e32 v171, v167, v167
	v_fmac_f32_e32 v116, v127, v127
	v_fmac_f32_e32 v117, v129, v129
	v_fmac_f32_e32 v126, v123, v123
	v_fmac_f32_e32 v128, v124, v124
	v_fmac_f32_e32 v168, v119, v119
	v_fmac_f32_e32 v169, v121, v121
	v_fmac_f32_e32 v170, v165, v165
	v_fmac_f32_e32 v171, v166, v166
	v_add_f32_e32 v116, v117, v116
	v_add_f32_e32 v117, v128, v126
	v_add_f32_e32 v126, v169, v168
	v_add_f32_e32 v127, v171, v170
	v_add_f32_e32 v116, v117, v116
	v_add_f32_e32 v117, v127, v126
	v_add_f32_e32 v126, v116, v117
	ds_bpermute_b32 v127, v162, v126
	v_cvt_pk_bf16_f32 v116, v122, v123
	v_cvt_pk_bf16_f32 v117, v124, v125
	global_store_dwordx4 v[172:173], v[114:117], off
	s_waitcnt lgkmcnt(0)
	s_nop 0
	v_add_f32_e32 v114, v126, v127
	v_lshlrev_b32_e32 v126, 2, v163
	ds_bpermute_b32 v115, v126, v114
	v_cvt_pk_bf16_f32 v116, v118, v119
	v_cvt_pk_bf16_f32 v117, v120, v121
	v_cvt_pk_bf16_f32 v118, v164, v165
	v_cvt_pk_bf16_f32 v119, v166, v167
	global_store_dwordx4 v[172:173], v[116:119], off offset:256
	s_and_saveexec_b64 s[20:21], s[0:1]
	s_cbranch_execz .LBB0_537
	v_lshlrev_b64 v[116:117], 7, v[148:149]
	v_lshl_add_u64 v[116:117], s[6:7], 0, v[116:117]
	v_lshl_add_u64 v[116:117], s[18:19], 2, v[116:117]
	s_lshl_b32 s40, s51, 2
	v_lshl_add_u64 v[116:117], v[116:117], 0, s[40:41]
	s_waitcnt lgkmcnt(0)
	v_add_f32_e32 v114, v114, v115
	global_store_dword v[116:117], v114, off

.LBB0_631:
	s_add_i32 s62, 0, 0x10000
	s_add_i32 s64, 0, 0x14000
	v_add_u32_e32 v142, s62, v246
	v_add_u32_e32 v158, s64, v246
	ds_read_b128 v[130:133], v142
	ds_read_b128 v[134:137], v142 offset:1024
	ds_read_b128 v[138:141], v142 offset:2048
	ds_read_b128 v[142:145], v142 offset:3072
	ds_read_b128 v[146:149], v158
	ds_read_b128 v[150:153], v158 offset:1024
	ds_read_b128 v[154:157], v158 offset:2048
	ds_read_b128 v[158:161], v158 offset:3072
	s_add_u32 s28, s26, 0xfffc0080
	s_addc_u32 s29, s27, -1
	s_cmp_eq_u32 s61, 12
	s_cselect_b32 s31, s3, s29
	s_cselect_b32 s30, s19, s28
	s_cselect_b32 s29, s17, s60
	s_cselect_b32 s28, s58, s59
	v_lshl_add_u64 v[192:193], s[26:27], 0, v[184:185]
	s_add_i32 m0, s25, 0xc000
	ds_read_b128 v[162:165], v247
	ds_read_b128 v[188:191], v247 offset:1024
	ds_read_b128 v[202:205], v247 offset:2048
	ds_read_b128 v[206:209], v247 offset:3072
	ds_read_b128 v[210:213], v247 offset:4096
	ds_read_b128 v[214:217], v247 offset:5120
	ds_read_b128 v[218:221], v247 offset:6144
	ds_read_b128 v[222:225], v247 offset:7168
	global_load_lds_dwordx4 v[192:193], off
	v_lshl_add_u64 v[192:193], s[26:27], 0, v[186:187]
	s_add_i32 m0, s25, 0xe000
	s_nop 0
	global_load_lds_dwordx4 v[192:193], off
	s_waitcnt vmcnt(8)
	s_waitcnt lgkmcnt(0)
	s_barrier
	s_waitcnt lgkmcnt(0)
	v_mfma_f32_16x16x32_bf16 v[126:129], v[130:133], v[162:165], v[126:129]
	v_mfma_f32_16x16x32_bf16 v[122:125], v[138:141], v[162:165], v[122:125]
	v_mfma_f32_16x16x32_bf16 v[110:113], v[130:133], v[202:205], v[110:113]
	v_mfma_f32_16x16x32_bf16 v[106:109], v[138:141], v[202:205], v[106:109]
	v_mfma_f32_16x16x32_bf16 v[94:97], v[130:133], v[210:213], v[94:97]
	v_mfma_f32_16x16x32_bf16 v[90:93], v[138:141], v[210:213], v[90:93]
	v_mfma_f32_16x16x32_bf16 v[78:81], v[130:133], v[218:221], v[78:81]
	v_mfma_f32_16x16x32_bf16 v[74:77], v[138:141], v[218:221], v[74:77]
	v_mfma_f32_16x16x32_bf16 v[126:129], v[134:137], v[188:191], v[126:129]
	v_mfma_f32_16x16x32_bf16 v[122:125], v[142:145], v[188:191], v[122:125]
	v_mfma_f32_16x16x32_bf16 v[110:113], v[134:137], v[206:209], v[110:113]
	v_mfma_f32_16x16x32_bf16 v[106:109], v[142:145], v[206:209], v[106:109]
	v_mfma_f32_16x16x32_bf16 v[94:97], v[134:137], v[214:217], v[94:97]
	v_mfma_f32_16x16x32_bf16 v[90:93], v[142:145], v[214:217], v[90:93]
	v_mfma_f32_16x16x32_bf16 v[78:81], v[134:137], v[222:225], v[78:81]
	v_mfma_f32_16x16x32_bf16 v[74:77], v[142:145], v[222:225], v[74:77]
	v_mfma_f32_16x16x32_bf16 v[118:121], v[146:149], v[162:165], v[118:121]
	v_mfma_f32_16x16x32_bf16 v[114:117], v[154:157], v[162:165], v[114:117]
	v_mfma_f32_16x16x32_bf16 v[102:105], v[146:149], v[202:205], v[102:105]
	v_mfma_f32_16x16x32_bf16 v[98:101], v[154:157], v[202:205], v[98:101]
	v_mfma_f32_16x16x32_bf16 v[86:89], v[146:149], v[210:213], v[86:89]
	v_mfma_f32_16x16x32_bf16 v[82:85], v[154:157], v[210:213], v[82:85]
	v_mfma_f32_16x16x32_bf16 v[70:73], v[146:149], v[218:221], v[70:73]
	v_mfma_f32_16x16x32_bf16 v[66:69], v[154:157], v[218:221], v[66:69]
	v_mfma_f32_16x16x32_bf16 v[118:121], v[150:153], v[188:191], v[118:121]
	v_mfma_f32_16x16x32_bf16 v[114:117], v[158:161], v[188:191], v[114:117]
	v_mfma_f32_16x16x32_bf16 v[102:105], v[150:153], v[206:209], v[102:105]
	v_mfma_f32_16x16x32_bf16 v[98:101], v[158:161], v[206:209], v[98:101]
	v_mfma_f32_16x16x32_bf16 v[86:89], v[150:153], v[214:217], v[86:89]
	v_mfma_f32_16x16x32_bf16 v[82:85], v[158:161], v[214:217], v[82:85]
	v_mfma_f32_16x16x32_bf16 v[70:73], v[150:153], v[222:225], v[70:73]
	v_mfma_f32_16x16x32_bf16 v[66:69], v[158:161], v[222:225], v[66:69]
	s_barrier
	s_add_i32 s62, s62, s45
	v_lshl_add_u64 v[192:193], s[28:29], 0, v[168:169]
	s_mov_b32 m0, s62
	ds_read_b128 v[162:165], v247 offset:16384
	ds_read_b128 v[188:191], v247 offset:17408
	ds_read_b128 v[202:205], v247 offset:18432
	ds_read_b128 v[206:209], v247 offset:19456
	ds_read_b128 v[210:213], v247 offset:20480
	ds_read_b128 v[214:217], v247 offset:21504
	ds_read_b128 v[218:221], v247 offset:22528
	ds_read_b128 v[222:225], v247 offset:23552
	global_load_lds_dwordx4 v[192:193], off
	s_add_i32 m0, s62, 0x2000
	s_add_u32 s62, s28, 0x40000
	v_lshl_add_u64 v[226:227], s[28:29], 0, v[172:173]
	s_addc_u32 s63, s29, 0
	s_add_i32 s64, s64, s45
	global_load_lds_dwordx4 v[226:227], off
	v_lshl_add_u64 v[228:229], s[62:63], 0, v[168:169]
	s_mov_b32 m0, s64
	v_lshl_add_u64 v[248:249], s[30:31], 0, v[170:171]
	global_load_lds_dwordx4 v[228:229], off
	v_lshl_add_u64 v[228:229], s[62:63], 0, v[172:173]
	s_add_i32 m0, s64, 0x2000
	s_nop 0
	global_load_lds_dwordx4 v[228:229], off
	v_lshl_add_u64 v[228:229], s[30:31], 0, v[166:167]
	s_mov_b32 m0, s25
	s_nop 0
	global_load_lds_dwordx4 v[228:229], off
	s_mov_b32 m0, s46
	s_nop 0
	global_load_lds_dwordx4 v[248:249], off
	s_waitcnt vmcnt(8)
	s_waitcnt lgkmcnt(0)
	s_barrier
	s_waitcnt lgkmcnt(0)
	v_mfma_f32_16x16x32_bf16 v[62:65], v[130:133], v[162:165], v[62:65]
	v_mfma_f32_16x16x32_bf16 v[58:61], v[138:141], v[162:165], v[58:61]
	v_mfma_f32_16x16x32_bf16 v[46:49], v[130:133], v[202:205], v[46:49]
	v_mfma_f32_16x16x32_bf16 v[42:45], v[138:141], v[202:205], v[42:45]
	v_mfma_f32_16x16x32_bf16 v[30:33], v[130:133], v[210:213], v[30:33]
	v_mfma_f32_16x16x32_bf16 v[26:29], v[138:141], v[210:213], v[26:29]
	v_mfma_f32_16x16x32_bf16 v[14:17], v[130:133], v[218:221], v[14:17]
	v_mfma_f32_16x16x32_bf16 v[10:13], v[138:141], v[218:221], v[10:13]
	v_mfma_f32_16x16x32_bf16 v[62:65], v[134:137], v[188:191], v[62:65]
	v_mfma_f32_16x16x32_bf16 v[58:61], v[142:145], v[188:191], v[58:61]
	v_mfma_f32_16x16x32_bf16 v[46:49], v[134:137], v[206:209], v[46:49]
	v_mfma_f32_16x16x32_bf16 v[42:45], v[142:145], v[206:209], v[42:45]
	v_mfma_f32_16x16x32_bf16 v[30:33], v[134:137], v[214:217], v[30:33]
	v_mfma_f32_16x16x32_bf16 v[26:29], v[142:145], v[214:217], v[26:29]
	v_mfma_f32_16x16x32_bf16 v[14:17], v[134:137], v[222:225], v[14:17]
	v_mfma_f32_16x16x32_bf16 v[10:13], v[142:145], v[222:225], v[10:13]
	v_mfma_f32_16x16x32_bf16 v[54:57], v[146:149], v[162:165], v[54:57]
	v_mfma_f32_16x16x32_bf16 v[50:53], v[154:157], v[162:165], v[50:53]
	v_mfma_f32_16x16x32_bf16 v[38:41], v[146:149], v[202:205], v[38:41]
	v_mfma_f32_16x16x32_bf16 v[34:37], v[154:157], v[202:205], v[34:37]
	v_mfma_f32_16x16x32_bf16 v[22:25], v[146:149], v[210:213], v[22:25]
	v_mfma_f32_16x16x32_bf16 v[18:21], v[154:157], v[210:213], v[18:21]
	v_mfma_f32_16x16x32_bf16 v[6:9], v[146:149], v[218:221], v[6:9]
	v_mfma_f32_16x16x32_bf16 v[2:5], v[154:157], v[218:221], v[2:5]
	v_mfma_f32_16x16x32_bf16 v[54:57], v[150:153], v[188:191], v[54:57]
	v_mfma_f32_16x16x32_bf16 v[50:53], v[158:161], v[188:191], v[50:53]
	v_mfma_f32_16x16x32_bf16 v[38:41], v[150:153], v[206:209], v[38:41]
	v_mfma_f32_16x16x32_bf16 v[34:37], v[158:161], v[206:209], v[34:37]
	v_mfma_f32_16x16x32_bf16 v[22:25], v[150:153], v[214:217], v[22:25]
	v_mfma_f32_16x16x32_bf16 v[18:21], v[158:161], v[214:217], v[18:21]
	v_mfma_f32_16x16x32_bf16 v[6:9], v[150:153], v[222:225], v[6:9]
	v_mfma_f32_16x16x32_bf16 v[2:5], v[158:161], v[222:225], v[2:5]
	s_barrier
	s_add_i32 s62, 0, 0x18000
	s_add_i32 s63, 0, 0x1c000
	v_add_u32_e32 v142, s62, v246
	v_add_u32_e32 v158, s63, v246
	ds_read_b128 v[130:133], v142
	ds_read_b128 v[134:137], v142 offset:1024
	ds_read_b128 v[138:141], v142 offset:2048
	ds_read_b128 v[142:145], v142 offset:3072
	ds_read_b128 v[146:149], v158
	ds_read_b128 v[150:153], v158 offset:1024
	ds_read_b128 v[154:157], v158 offset:2048
	ds_read_b128 v[158:161], v158 offset:3072
	s_add_u32 s30, s30, 0x40000
	s_addc_u32 s31, s31, 0
	s_mov_b32 m0, s47
	v_lshl_add_u64 v[250:251], s[30:31], 0, v[166:167]
	ds_read_b128 v[162:165], v247 offset:32768
	ds_read_b128 v[188:191], v247 offset:33792
	ds_read_b128 v[202:205], v247 offset:34816
	ds_read_b128 v[206:209], v247 offset:35840
	ds_read_b128 v[210:213], v247 offset:36864
	ds_read_b128 v[214:217], v247 offset:37888
	ds_read_b128 v[218:221], v247 offset:38912
	ds_read_b128 v[222:225], v247 offset:39936
	global_load_lds_dwordx4 v[250:251], off
	v_lshl_add_u64 v[250:251], s[30:31], 0, v[170:171]
	s_mov_b32 m0, s48
	s_nop 0
	global_load_lds_dwordx4 v[250:251], off
	s_waitcnt vmcnt(8)
	s_waitcnt lgkmcnt(0)
	s_barrier
	s_waitcnt lgkmcnt(0)
	v_mfma_f32_16x16x32_bf16 v[126:129], v[130:133], v[162:165], v[126:129]
	v_mfma_f32_16x16x32_bf16 v[122:125], v[138:141], v[162:165], v[122:125]
	v_mfma_f32_16x16x32_bf16 v[110:113], v[130:133], v[202:205], v[110:113]
	v_mfma_f32_16x16x32_bf16 v[106:109], v[138:141], v[202:205], v[106:109]
	v_mfma_f32_16x16x32_bf16 v[94:97], v[130:133], v[210:213], v[94:97]
	v_mfma_f32_16x16x32_bf16 v[90:93], v[138:141], v[210:213], v[90:93]
	v_mfma_f32_16x16x32_bf16 v[78:81], v[130:133], v[218:221], v[78:81]
	v_mfma_f32_16x16x32_bf16 v[74:77], v[138:141], v[218:221], v[74:77]
	v_mfma_f32_16x16x32_bf16 v[126:129], v[134:137], v[188:191], v[126:129]
	v_mfma_f32_16x16x32_bf16 v[122:125], v[142:145], v[188:191], v[122:125]
	v_mfma_f32_16x16x32_bf16 v[110:113], v[134:137], v[206:209], v[110:113]
	v_mfma_f32_16x16x32_bf16 v[106:109], v[142:145], v[206:209], v[106:109]
	v_mfma_f32_16x16x32_bf16 v[94:97], v[134:137], v[214:217], v[94:97]
	v_mfma_f32_16x16x32_bf16 v[90:93], v[142:145], v[214:217], v[90:93]
	v_mfma_f32_16x16x32_bf16 v[78:81], v[134:137], v[222:225], v[78:81]
	v_mfma_f32_16x16x32_bf16 v[74:77], v[142:145], v[222:225], v[74:77]
	v_mfma_f32_16x16x32_bf16 v[118:121], v[146:149], v[162:165], v[118:121]
	v_mfma_f32_16x16x32_bf16 v[114:117], v[154:157], v[162:165], v[114:117]
	v_mfma_f32_16x16x32_bf16 v[102:105], v[146:149], v[202:205], v[102:105]
	v_mfma_f32_16x16x32_bf16 v[98:101], v[154:157], v[202:205], v[98:101]
	v_mfma_f32_16x16x32_bf16 v[86:89], v[146:149], v[210:213], v[86:89]
	v_mfma_f32_16x16x32_bf16 v[82:85], v[154:157], v[210:213], v[82:85]
	v_mfma_f32_16x16x32_bf16 v[70:73], v[146:149], v[218:221], v[70:73]
	v_mfma_f32_16x16x32_bf16 v[66:69], v[154:157], v[218:221], v[66:69]
	v_mfma_f32_16x16x32_bf16 v[118:121], v[150:153], v[188:191], v[118:121]
	v_mfma_f32_16x16x32_bf16 v[114:117], v[158:161], v[188:191], v[114:117]
	v_mfma_f32_16x16x32_bf16 v[102:105], v[150:153], v[206:209], v[102:105]
	v_mfma_f32_16x16x32_bf16 v[98:101], v[158:161], v[206:209], v[98:101]
	v_mfma_f32_16x16x32_bf16 v[86:89], v[150:153], v[214:217], v[86:89]
	v_mfma_f32_16x16x32_bf16 v[82:85], v[158:161], v[214:217], v[82:85]
	v_mfma_f32_16x16x32_bf16 v[70:73], v[150:153], v[222:225], v[70:73]
	v_mfma_f32_16x16x32_bf16 v[66:69], v[158:161], v[222:225], v[66:69]
	s_barrier
	s_add_i32 s30, s62, s45
	v_lshl_add_u64 v[192:193], v[192:193], 0, s[92:93]
	s_mov_b32 m0, s30
	ds_read_b128 v[162:165], v247 offset:49152
	ds_read_b128 v[188:191], v247 offset:50176
	ds_read_b128 v[202:205], v247 offset:51200
	ds_read_b128 v[206:209], v247 offset:52224
	ds_read_b128 v[210:213], v247 offset:53248
	ds_read_b128 v[214:217], v247 offset:54272
	ds_read_b128 v[218:221], v247 offset:55296
	ds_read_b128 v[222:225], v247 offset:56320
	global_load_lds_dwordx4 v[192:193], off
	s_add_i32 m0, s30, 0x2000
	s_add_u32 s28, s28, 0x40080
	v_lshl_add_u64 v[192:193], v[226:227], 0, s[92:93]
	s_addc_u32 s29, s29, 0
	s_add_i32 s30, s63, s45
	global_load_lds_dwordx4 v[192:193], off
	v_lshl_add_u64 v[192:193], s[28:29], 0, v[168:169]
	s_mov_b32 m0, s30
	s_nop 0
	global_load_lds_dwordx4 v[192:193], off
	v_lshl_add_u64 v[192:193], s[28:29], 0, v[172:173]
	s_add_i32 m0, s30, 0x2000
	s_nop 0
	global_load_lds_dwordx4 v[192:193], off
	v_lshl_add_u64 v[192:193], v[228:229], 0, s[92:93]
	s_mov_b32 m0, s52
	s_nop 0
	global_load_lds_dwordx4 v[192:193], off
	v_lshl_add_u64 v[192:193], v[248:249], 0, s[92:93]
	s_mov_b32 m0, s53
	s_nop 0
	global_load_lds_dwordx4 v[192:193], off
	s_waitcnt vmcnt(8)
	s_waitcnt lgkmcnt(0)
	s_barrier
	s_waitcnt lgkmcnt(0)
	v_mfma_f32_16x16x32_bf16 v[62:65], v[130:133], v[162:165], v[62:65]
	v_mfma_f32_16x16x32_bf16 v[58:61], v[138:141], v[162:165], v[58:61]
	v_mfma_f32_16x16x32_bf16 v[46:49], v[130:133], v[202:205], v[46:49]
	v_mfma_f32_16x16x32_bf16 v[42:45], v[138:141], v[202:205], v[42:45]
	v_mfma_f32_16x16x32_bf16 v[30:33], v[130:133], v[210:213], v[30:33]
	v_mfma_f32_16x16x32_bf16 v[26:29], v[138:141], v[210:213], v[26:29]
	v_mfma_f32_16x16x32_bf16 v[14:17], v[130:133], v[218:221], v[14:17]
	v_mfma_f32_16x16x32_bf16 v[10:13], v[138:141], v[218:221], v[10:13]
	v_mfma_f32_16x16x32_bf16 v[62:65], v[134:137], v[188:191], v[62:65]
	v_mfma_f32_16x16x32_bf16 v[58:61], v[142:145], v[188:191], v[58:61]
	v_mfma_f32_16x16x32_bf16 v[46:49], v[134:137], v[206:209], v[46:49]
	v_mfma_f32_16x16x32_bf16 v[42:45], v[142:145], v[206:209], v[42:45]
	v_mfma_f32_16x16x32_bf16 v[30:33], v[134:137], v[214:217], v[30:33]
	v_mfma_f32_16x16x32_bf16 v[26:29], v[142:145], v[214:217], v[26:29]
	v_mfma_f32_16x16x32_bf16 v[14:17], v[134:137], v[222:225], v[14:17]
	v_mfma_f32_16x16x32_bf16 v[10:13], v[142:145], v[222:225], v[10:13]
	v_mfma_f32_16x16x32_bf16 v[54:57], v[146:149], v[162:165], v[54:57]
	v_mfma_f32_16x16x32_bf16 v[50:53], v[154:157], v[162:165], v[50:53]
	v_mfma_f32_16x16x32_bf16 v[38:41], v[146:149], v[202:205], v[38:41]
	v_mfma_f32_16x16x32_bf16 v[34:37], v[154:157], v[202:205], v[34:37]
	v_mfma_f32_16x16x32_bf16 v[22:25], v[146:149], v[210:213], v[22:25]
	v_mfma_f32_16x16x32_bf16 v[18:21], v[154:157], v[210:213], v[18:21]
	v_mfma_f32_16x16x32_bf16 v[6:9], v[146:149], v[218:221], v[6:9]
	v_mfma_f32_16x16x32_bf16 v[2:5], v[154:157], v[218:221], v[2:5]
	v_mfma_f32_16x16x32_bf16 v[54:57], v[150:153], v[188:191], v[54:57]
	v_mfma_f32_16x16x32_bf16 v[50:53], v[158:161], v[188:191], v[50:53]
	v_mfma_f32_16x16x32_bf16 v[38:41], v[150:153], v[206:209], v[38:41]
	v_mfma_f32_16x16x32_bf16 v[34:37], v[158:161], v[206:209], v[34:37]
	v_mfma_f32_16x16x32_bf16 v[22:25], v[150:153], v[214:217], v[22:25]
	v_mfma_f32_16x16x32_bf16 v[18:21], v[158:161], v[214:217], v[18:21]
	v_mfma_f32_16x16x32_bf16 v[6:9], v[150:153], v[222:225], v[6:9]
	v_mfma_f32_16x16x32_bf16 v[2:5], v[158:161], v[222:225], v[2:5]
	s_add_i32 s61, s61, 2
	s_add_u32 s26, s26, 0x100
	s_addc_u32 s27, s27, 0
	s_add_u32 s59, s59, 0x100
	s_addc_u32 s60, s60, 0
	s_cmp_gt_u32 s61, 13
	s_barrier
	s_cbranch_scc0 .LBB0_631
	s_and_b64 vcc, exec, s[14:15]
	s_cbranch_vccnz .LBB0_636
	s_cmp_gt_i32 s2, 4
	s_mov_b64 s[26:27], -1
	s_cbranch_scc0 .LBB0_637

.LBB0_939:
	s_add_i32 s52, 0, 0x10000
	s_add_i32 s54, 0, 0x14000
	v_add_u32_e32 v142, s52, v167
	v_add_u32_e32 v164, s54, v167
	ds_read_b128 v[130:133], v142
	ds_read_b128 v[134:137], v142 offset:1024
	ds_read_b128 v[138:141], v142 offset:2048
	ds_read_b128 v[142:145], v142 offset:3072
	ds_read_b128 v[156:159], v164
	ds_read_b128 v[160:163], v164 offset:1024
	ds_read_b128 v[170:173], v164 offset:2048
	ds_read_b128 v[174:177], v164 offset:3072
	s_add_u32 s24, s22, 0xfffc0080
	s_addc_u32 s25, s23, -1
	s_cmp_eq_u32 s51, 12
	s_cselect_b32 s27, s13, s25
	s_cselect_b32 s26, s19, s24
	s_cselect_b32 s25, s11, s50
	s_cselect_b32 s24, s21, s49
	v_lshl_add_u64 v[164:165], s[22:23], 0, v[152:153]
	s_add_i32 m0, s38, 0xc000
	ds_read_b128 v[178:181], v169
	ds_read_b128 v[182:185], v169 offset:1024
	ds_read_b128 v[186:189], v169 offset:2048
	ds_read_b128 v[190:193], v169 offset:3072
	ds_read_b128 v[202:205], v169 offset:4096
	ds_read_b128 v[206:209], v169 offset:5120
	ds_read_b128 v[210:213], v169 offset:6144
	ds_read_b128 v[214:217], v169 offset:7168
	global_load_lds_dwordx4 v[164:165], off
	v_lshl_add_u64 v[164:165], s[22:23], 0, v[154:155]
	s_add_i32 m0, s38, 0xe000
	s_nop 0
	global_load_lds_dwordx4 v[164:165], off
	s_waitcnt vmcnt(8)
	s_waitcnt lgkmcnt(0)
	s_barrier
	s_waitcnt lgkmcnt(0)
	v_mfma_f32_16x16x32_bf16 v[126:129], v[130:133], v[178:181], v[126:129]
	v_mfma_f32_16x16x32_bf16 v[122:125], v[138:141], v[178:181], v[122:125]
	v_mfma_f32_16x16x32_bf16 v[110:113], v[130:133], v[186:189], v[110:113]
	v_mfma_f32_16x16x32_bf16 v[106:109], v[138:141], v[186:189], v[106:109]
	v_mfma_f32_16x16x32_bf16 v[94:97], v[130:133], v[202:205], v[94:97]
	v_mfma_f32_16x16x32_bf16 v[90:93], v[138:141], v[202:205], v[90:93]
	v_mfma_f32_16x16x32_bf16 v[78:81], v[130:133], v[210:213], v[78:81]
	v_mfma_f32_16x16x32_bf16 v[74:77], v[138:141], v[210:213], v[74:77]
	v_mfma_f32_16x16x32_bf16 v[126:129], v[134:137], v[182:185], v[126:129]
	v_mfma_f32_16x16x32_bf16 v[122:125], v[142:145], v[182:185], v[122:125]
	v_mfma_f32_16x16x32_bf16 v[110:113], v[134:137], v[190:193], v[110:113]
	v_mfma_f32_16x16x32_bf16 v[106:109], v[142:145], v[190:193], v[106:109]
	v_mfma_f32_16x16x32_bf16 v[94:97], v[134:137], v[206:209], v[94:97]
	v_mfma_f32_16x16x32_bf16 v[90:93], v[142:145], v[206:209], v[90:93]
	v_mfma_f32_16x16x32_bf16 v[78:81], v[134:137], v[214:217], v[78:81]
	v_mfma_f32_16x16x32_bf16 v[74:77], v[142:145], v[214:217], v[74:77]
	v_mfma_f32_16x16x32_bf16 v[118:121], v[156:159], v[178:181], v[118:121]
	v_mfma_f32_16x16x32_bf16 v[114:117], v[170:173], v[178:181], v[114:117]
	v_mfma_f32_16x16x32_bf16 v[102:105], v[156:159], v[186:189], v[102:105]
	v_mfma_f32_16x16x32_bf16 v[98:101], v[170:173], v[186:189], v[98:101]
	v_mfma_f32_16x16x32_bf16 v[86:89], v[156:159], v[202:205], v[86:89]
	v_mfma_f32_16x16x32_bf16 v[82:85], v[170:173], v[202:205], v[82:85]
	v_mfma_f32_16x16x32_bf16 v[70:73], v[156:159], v[210:213], v[70:73]
	v_mfma_f32_16x16x32_bf16 v[66:69], v[170:173], v[210:213], v[66:69]
	v_mfma_f32_16x16x32_bf16 v[118:121], v[160:163], v[182:185], v[118:121]
	v_mfma_f32_16x16x32_bf16 v[114:117], v[174:177], v[182:185], v[114:117]
	v_mfma_f32_16x16x32_bf16 v[102:105], v[160:163], v[190:193], v[102:105]
	v_mfma_f32_16x16x32_bf16 v[98:101], v[174:177], v[190:193], v[98:101]
	v_mfma_f32_16x16x32_bf16 v[86:89], v[160:163], v[206:209], v[86:89]
	v_mfma_f32_16x16x32_bf16 v[82:85], v[174:177], v[206:209], v[82:85]
	v_mfma_f32_16x16x32_bf16 v[70:73], v[160:163], v[214:217], v[70:73]
	v_mfma_f32_16x16x32_bf16 v[66:69], v[174:177], v[214:217], v[66:69]
	s_barrier
	s_add_i32 s52, s52, s37
	v_lshl_add_u64 v[164:165], s[24:25], 0, v[194:195]
	s_mov_b32 m0, s52
	ds_read_b128 v[178:181], v169 offset:16384
	ds_read_b128 v[182:185], v169 offset:17408
	ds_read_b128 v[186:189], v169 offset:18432
	ds_read_b128 v[190:193], v169 offset:19456
	ds_read_b128 v[202:205], v169 offset:20480
	ds_read_b128 v[206:209], v169 offset:21504
	ds_read_b128 v[210:213], v169 offset:22528
	ds_read_b128 v[214:217], v169 offset:23552
	global_load_lds_dwordx4 v[164:165], off
	s_add_i32 m0, s52, 0x2000
	s_add_u32 s52, s24, 0x40000
	v_lshl_add_u64 v[218:219], s[24:25], 0, v[150:151]
	s_addc_u32 s53, s25, 0
	s_add_i32 s54, s54, s37
	global_load_lds_dwordx4 v[218:219], off
	v_lshl_add_u64 v[220:221], s[52:53], 0, v[194:195]
	s_mov_b32 m0, s54
	v_lshl_add_u64 v[222:223], s[26:27], 0, v[148:149]
	global_load_lds_dwordx4 v[220:221], off
	v_lshl_add_u64 v[220:221], s[52:53], 0, v[150:151]
	s_add_i32 m0, s54, 0x2000
	s_nop 0
	global_load_lds_dwordx4 v[220:221], off
	v_lshl_add_u64 v[220:221], s[26:27], 0, v[146:147]
	s_mov_b32 m0, s38
	s_nop 0
	global_load_lds_dwordx4 v[220:221], off
	s_mov_b32 m0, s39
	s_nop 0
	global_load_lds_dwordx4 v[222:223], off
	s_waitcnt vmcnt(8)
	s_waitcnt lgkmcnt(0)
	s_barrier
	s_waitcnt lgkmcnt(0)
	v_mfma_f32_16x16x32_bf16 v[62:65], v[130:133], v[178:181], v[62:65]
	v_mfma_f32_16x16x32_bf16 v[58:61], v[138:141], v[178:181], v[58:61]
	v_mfma_f32_16x16x32_bf16 v[46:49], v[130:133], v[186:189], v[46:49]
	v_mfma_f32_16x16x32_bf16 v[42:45], v[138:141], v[186:189], v[42:45]
	v_mfma_f32_16x16x32_bf16 v[30:33], v[130:133], v[202:205], v[30:33]
	v_mfma_f32_16x16x32_bf16 v[26:29], v[138:141], v[202:205], v[26:29]
	v_mfma_f32_16x16x32_bf16 v[14:17], v[130:133], v[210:213], v[14:17]
	v_mfma_f32_16x16x32_bf16 v[10:13], v[138:141], v[210:213], v[10:13]
	v_mfma_f32_16x16x32_bf16 v[62:65], v[134:137], v[182:185], v[62:65]
	v_mfma_f32_16x16x32_bf16 v[58:61], v[142:145], v[182:185], v[58:61]
	v_mfma_f32_16x16x32_bf16 v[46:49], v[134:137], v[190:193], v[46:49]
	v_mfma_f32_16x16x32_bf16 v[42:45], v[142:145], v[190:193], v[42:45]
	v_mfma_f32_16x16x32_bf16 v[30:33], v[134:137], v[206:209], v[30:33]
	v_mfma_f32_16x16x32_bf16 v[26:29], v[142:145], v[206:209], v[26:29]
	v_mfma_f32_16x16x32_bf16 v[14:17], v[134:137], v[214:217], v[14:17]
	v_mfma_f32_16x16x32_bf16 v[10:13], v[142:145], v[214:217], v[10:13]
	v_mfma_f32_16x16x32_bf16 v[54:57], v[156:159], v[178:181], v[54:57]
	v_mfma_f32_16x16x32_bf16 v[50:53], v[170:173], v[178:181], v[50:53]
	v_mfma_f32_16x16x32_bf16 v[38:41], v[156:159], v[186:189], v[38:41]
	v_mfma_f32_16x16x32_bf16 v[34:37], v[170:173], v[186:189], v[34:37]
	v_mfma_f32_16x16x32_bf16 v[22:25], v[156:159], v[202:205], v[22:25]
	v_mfma_f32_16x16x32_bf16 v[18:21], v[170:173], v[202:205], v[18:21]
	v_mfma_f32_16x16x32_bf16 v[6:9], v[156:159], v[210:213], v[6:9]
	v_mfma_f32_16x16x32_bf16 v[2:5], v[170:173], v[210:213], v[2:5]
	v_mfma_f32_16x16x32_bf16 v[54:57], v[160:163], v[182:185], v[54:57]
	v_mfma_f32_16x16x32_bf16 v[50:53], v[174:177], v[182:185], v[50:53]
	v_mfma_f32_16x16x32_bf16 v[38:41], v[160:163], v[190:193], v[38:41]
	v_mfma_f32_16x16x32_bf16 v[34:37], v[174:177], v[190:193], v[34:37]
	v_mfma_f32_16x16x32_bf16 v[22:25], v[160:163], v[206:209], v[22:25]
	v_mfma_f32_16x16x32_bf16 v[18:21], v[174:177], v[206:209], v[18:21]
	v_mfma_f32_16x16x32_bf16 v[6:9], v[160:163], v[214:217], v[6:9]
	v_mfma_f32_16x16x32_bf16 v[2:5], v[174:177], v[214:217], v[2:5]
	s_barrier
	s_add_i32 s52, 0, 0x18000
	s_add_i32 s53, 0, 0x1c000
	v_add_u32_e32 v142, s52, v167
	v_add_u32_e32 v174, s53, v167
	ds_read_b128 v[130:133], v142
	ds_read_b128 v[134:137], v142 offset:1024
	ds_read_b128 v[138:141], v142 offset:2048
	ds_read_b128 v[142:145], v142 offset:3072
	ds_read_b128 v[156:159], v174
	ds_read_b128 v[160:163], v174 offset:1024
	ds_read_b128 v[170:173], v174 offset:2048
	ds_read_b128 v[174:177], v174 offset:3072
	s_add_u32 s26, s26, 0x40000
	s_addc_u32 s27, s27, 0
	s_mov_b32 m0, s42
	v_lshl_add_u64 v[224:225], s[26:27], 0, v[146:147]
	ds_read_b128 v[178:181], v169 offset:32768
	ds_read_b128 v[182:185], v169 offset:33792
	ds_read_b128 v[186:189], v169 offset:34816
	ds_read_b128 v[190:193], v169 offset:35840
	ds_read_b128 v[202:205], v169 offset:36864
	ds_read_b128 v[206:209], v169 offset:37888
	ds_read_b128 v[210:213], v169 offset:38912
	ds_read_b128 v[214:217], v169 offset:39936
	global_load_lds_dwordx4 v[224:225], off
	v_lshl_add_u64 v[224:225], s[26:27], 0, v[148:149]
	s_mov_b32 m0, s43
	s_nop 0
	global_load_lds_dwordx4 v[224:225], off
	s_waitcnt vmcnt(8)
	s_waitcnt lgkmcnt(0)
	s_barrier
	s_waitcnt lgkmcnt(0)
	v_mfma_f32_16x16x32_bf16 v[126:129], v[130:133], v[178:181], v[126:129]
	v_mfma_f32_16x16x32_bf16 v[122:125], v[138:141], v[178:181], v[122:125]
	v_mfma_f32_16x16x32_bf16 v[110:113], v[130:133], v[186:189], v[110:113]
	v_mfma_f32_16x16x32_bf16 v[106:109], v[138:141], v[186:189], v[106:109]
	v_mfma_f32_16x16x32_bf16 v[94:97], v[130:133], v[202:205], v[94:97]
	v_mfma_f32_16x16x32_bf16 v[90:93], v[138:141], v[202:205], v[90:93]
	v_mfma_f32_16x16x32_bf16 v[78:81], v[130:133], v[210:213], v[78:81]
	v_mfma_f32_16x16x32_bf16 v[74:77], v[138:141], v[210:213], v[74:77]
	v_mfma_f32_16x16x32_bf16 v[126:129], v[134:137], v[182:185], v[126:129]
	v_mfma_f32_16x16x32_bf16 v[122:125], v[142:145], v[182:185], v[122:125]
	v_mfma_f32_16x16x32_bf16 v[110:113], v[134:137], v[190:193], v[110:113]
	v_mfma_f32_16x16x32_bf16 v[106:109], v[142:145], v[190:193], v[106:109]
	v_mfma_f32_16x16x32_bf16 v[94:97], v[134:137], v[206:209], v[94:97]
	v_mfma_f32_16x16x32_bf16 v[90:93], v[142:145], v[206:209], v[90:93]
	v_mfma_f32_16x16x32_bf16 v[78:81], v[134:137], v[214:217], v[78:81]
	v_mfma_f32_16x16x32_bf16 v[74:77], v[142:145], v[214:217], v[74:77]
	v_mfma_f32_16x16x32_bf16 v[118:121], v[156:159], v[178:181], v[118:121]
	v_mfma_f32_16x16x32_bf16 v[114:117], v[170:173], v[178:181], v[114:117]
	v_mfma_f32_16x16x32_bf16 v[102:105], v[156:159], v[186:189], v[102:105]
	v_mfma_f32_16x16x32_bf16 v[98:101], v[170:173], v[186:189], v[98:101]
	v_mfma_f32_16x16x32_bf16 v[86:89], v[156:159], v[202:205], v[86:89]
	v_mfma_f32_16x16x32_bf16 v[82:85], v[170:173], v[202:205], v[82:85]
	v_mfma_f32_16x16x32_bf16 v[70:73], v[156:159], v[210:213], v[70:73]
	v_mfma_f32_16x16x32_bf16 v[66:69], v[170:173], v[210:213], v[66:69]
	v_mfma_f32_16x16x32_bf16 v[118:121], v[160:163], v[182:185], v[118:121]
	v_mfma_f32_16x16x32_bf16 v[114:117], v[174:177], v[182:185], v[114:117]
	v_mfma_f32_16x16x32_bf16 v[102:105], v[160:163], v[190:193], v[102:105]
	v_mfma_f32_16x16x32_bf16 v[98:101], v[174:177], v[190:193], v[98:101]
	v_mfma_f32_16x16x32_bf16 v[86:89], v[160:163], v[206:209], v[86:89]
	v_mfma_f32_16x16x32_bf16 v[82:85], v[174:177], v[206:209], v[82:85]
	v_mfma_f32_16x16x32_bf16 v[70:73], v[160:163], v[214:217], v[70:73]
	v_mfma_f32_16x16x32_bf16 v[66:69], v[174:177], v[214:217], v[66:69]
	s_barrier
	s_add_i32 s26, s52, s37
	v_lshl_add_u64 v[164:165], v[164:165], 0, s[92:93]
	s_mov_b32 m0, s26
	ds_read_b128 v[178:181], v169 offset:49152
	ds_read_b128 v[182:185], v169 offset:50176
	ds_read_b128 v[186:189], v169 offset:51200
	ds_read_b128 v[190:193], v169 offset:52224
	ds_read_b128 v[202:205], v169 offset:53248
	ds_read_b128 v[206:209], v169 offset:54272
	ds_read_b128 v[210:213], v169 offset:55296
	ds_read_b128 v[214:217], v169 offset:56320
	global_load_lds_dwordx4 v[164:165], off
	s_add_i32 m0, s26, 0x2000
	s_add_u32 s24, s24, 0x40080
	v_lshl_add_u64 v[164:165], v[218:219], 0, s[92:93]
	s_addc_u32 s25, s25, 0
	s_add_i32 s26, s53, s37
	global_load_lds_dwordx4 v[164:165], off
	v_lshl_add_u64 v[164:165], s[24:25], 0, v[194:195]
	s_mov_b32 m0, s26
	s_nop 0
	global_load_lds_dwordx4 v[164:165], off
	v_lshl_add_u64 v[164:165], s[24:25], 0, v[150:151]
	s_add_i32 m0, s26, 0x2000
	s_nop 0
	global_load_lds_dwordx4 v[164:165], off
	v_lshl_add_u64 v[164:165], v[220:221], 0, s[92:93]
	s_mov_b32 m0, s45
	s_nop 0
	global_load_lds_dwordx4 v[164:165], off
	v_lshl_add_u64 v[164:165], v[222:223], 0, s[92:93]
	s_mov_b32 m0, s46
	s_nop 0
	global_load_lds_dwordx4 v[164:165], off
	s_waitcnt vmcnt(8)
	s_waitcnt lgkmcnt(0)
	s_barrier
	s_waitcnt lgkmcnt(0)
	v_mfma_f32_16x16x32_bf16 v[62:65], v[130:133], v[178:181], v[62:65]
	v_mfma_f32_16x16x32_bf16 v[58:61], v[138:141], v[178:181], v[58:61]
	v_mfma_f32_16x16x32_bf16 v[46:49], v[130:133], v[186:189], v[46:49]
	v_mfma_f32_16x16x32_bf16 v[42:45], v[138:141], v[186:189], v[42:45]
	v_mfma_f32_16x16x32_bf16 v[30:33], v[130:133], v[202:205], v[30:33]
	v_mfma_f32_16x16x32_bf16 v[26:29], v[138:141], v[202:205], v[26:29]
	v_mfma_f32_16x16x32_bf16 v[14:17], v[130:133], v[210:213], v[14:17]
	v_mfma_f32_16x16x32_bf16 v[10:13], v[138:141], v[210:213], v[10:13]
	v_mfma_f32_16x16x32_bf16 v[62:65], v[134:137], v[182:185], v[62:65]
	v_mfma_f32_16x16x32_bf16 v[58:61], v[142:145], v[182:185], v[58:61]
	v_mfma_f32_16x16x32_bf16 v[46:49], v[134:137], v[190:193], v[46:49]
	v_mfma_f32_16x16x32_bf16 v[42:45], v[142:145], v[190:193], v[42:45]
	v_mfma_f32_16x16x32_bf16 v[30:33], v[134:137], v[206:209], v[30:33]
	v_mfma_f32_16x16x32_bf16 v[26:29], v[142:145], v[206:209], v[26:29]
	v_mfma_f32_16x16x32_bf16 v[14:17], v[134:137], v[214:217], v[14:17]
	v_mfma_f32_16x16x32_bf16 v[10:13], v[142:145], v[214:217], v[10:13]
	v_mfma_f32_16x16x32_bf16 v[54:57], v[156:159], v[178:181], v[54:57]
	v_mfma_f32_16x16x32_bf16 v[50:53], v[170:173], v[178:181], v[50:53]
	v_mfma_f32_16x16x32_bf16 v[38:41], v[156:159], v[186:189], v[38:41]
	v_mfma_f32_16x16x32_bf16 v[34:37], v[170:173], v[186:189], v[34:37]
	v_mfma_f32_16x16x32_bf16 v[22:25], v[156:159], v[202:205], v[22:25]
	v_mfma_f32_16x16x32_bf16 v[18:21], v[170:173], v[202:205], v[18:21]
	v_mfma_f32_16x16x32_bf16 v[6:9], v[156:159], v[210:213], v[6:9]
	v_mfma_f32_16x16x32_bf16 v[2:5], v[170:173], v[210:213], v[2:5]
	v_mfma_f32_16x16x32_bf16 v[54:57], v[160:163], v[182:185], v[54:57]
	v_mfma_f32_16x16x32_bf16 v[50:53], v[174:177], v[182:185], v[50:53]
	v_mfma_f32_16x16x32_bf16 v[38:41], v[160:163], v[190:193], v[38:41]
	v_mfma_f32_16x16x32_bf16 v[34:37], v[174:177], v[190:193], v[34:37]
	v_mfma_f32_16x16x32_bf16 v[22:25], v[160:163], v[206:209], v[22:25]
	v_mfma_f32_16x16x32_bf16 v[18:21], v[174:177], v[206:209], v[18:21]
	v_mfma_f32_16x16x32_bf16 v[6:9], v[160:163], v[214:217], v[6:9]
	v_mfma_f32_16x16x32_bf16 v[2:5], v[174:177], v[214:217], v[2:5]
	s_add_i32 s51, s51, 2
	s_add_u32 s22, s22, 0x100
	s_addc_u32 s23, s23, 0
	s_add_u32 s49, s49, 0x100
	s_addc_u32 s50, s50, 0
	s_cmp_gt_u32 s51, 13
	s_barrier
	s_cbranch_scc0 .LBB0_939
	v_lshl_add_u32 v156, s20, 8, v166
	v_lshl_or_b32 v158, s18, 8, v168
	v_ashrrev_i32_e32 v157, 31, v156
	v_lshlrev_b64 v[130:131], 11, v[156:157]
	v_ashrrev_i32_e32 v159, 31, v158
	v_lshl_add_u64 v[130:131], s[8:9], 0, v[130:131]
	v_lshlrev_b64 v[132:133], 1, v[158:159]
	v_lshl_add_u64 v[164:165], v[130:131], 0, v[132:133]
	global_load_dwordx4 v[142:145], v[164:165], off
	global_load_dwordx4 v[138:141], v[164:165], off offset:256
	v_or_b32_e32 v160, 16, v156
	v_ashrrev_i32_e32 v161, 31, v160
	v_lshlrev_b64 v[130:131], 11, v[160:161]
	v_lshl_add_u64 v[130:131], s[8:9], 0, v[130:131]
	v_lshl_add_u64 v[162:163], v[130:131], 0, v[132:133]
	global_load_dwordx4 v[134:137], v[162:163], off
	global_load_dwordx4 v[130:133], v[162:163], off offset:256
	v_and_b32_e32 v171, 64, v1
	v_xor_b32_e32 v170, 16, v1
	v_add_u32_e32 v171, 64, v171
	v_xor_b32_e32 v172, 32, v1
	v_cmp_lt_i32_e32 vcc, v170, v171
	s_lshl_b32 s18, s18, 2
	s_ashr_i32 s19, s18, 31
	v_cndmask_b32_e32 v170, v1, v170, vcc
	v_cmp_lt_i32_e32 vcc, v172, v171
	v_lshlrev_b32_e32 v170, 2, v170
	s_waitcnt vmcnt(0)
	v_and_b32_e32 v173, 0xffff0000, v142
	v_cndmask_b32_e32 v171, v1, v172, vcc
	v_lshlrev_b32_e32 v172, 16, v142
	v_lshlrev_b32_e32 v142, 16, v143
	v_and_b32_e32 v143, 0xffff0000, v143
	v_lshlrev_b32_e32 v174, 16, v144
	v_and_b32_e32 v175, 0xffff0000, v144
	v_lshlrev_b32_e32 v144, 16, v145
	v_and_b32_e32 v145, 0xffff0000, v145
	v_lshlrev_b32_e32 v176, 16, v138
	v_and_b32_e32 v177, 0xffff0000, v138
	v_lshlrev_b32_e32 v138, 16, v139
	v_and_b32_e32 v139, 0xffff0000, v139
	v_lshlrev_b32_e32 v178, 16, v140
	v_and_b32_e32 v179, 0xffff0000, v140
	v_lshlrev_b32_e32 v140, 16, v141
	v_and_b32_e32 v141, 0xffff0000, v141
	v_pk_add_f32 v[128:129], v[128:129], v[142:143]
	v_pk_add_f32 v[126:127], v[126:127], v[172:173]
	v_pk_add_f32 v[122:123], v[122:123], v[174:175]
	v_pk_add_f32 v[124:125], v[124:125], v[144:145]
	v_pk_add_f32 v[120:121], v[120:121], v[138:139]
	v_pk_add_f32 v[118:119], v[118:119], v[176:177]
	v_pk_add_f32 v[138:139], v[114:115], v[178:179]
	v_pk_add_f32 v[140:141], v[116:117], v[140:141]
	v_cvt_pk_bf16_f32 v114, v126, v127
	v_cvt_pk_bf16_f32 v115, v128, v129
	v_mul_f32_e32 v116, v126, v126
	v_mul_f32_e32 v117, v128, v128
	v_mul_f32_e32 v126, v122, v122
	v_mul_f32_e32 v128, v125, v125
	v_mul_f32_e32 v142, v118, v118
	v_mul_f32_e32 v143, v120, v120
	v_mul_f32_e32 v144, v138, v138
	v_mul_f32_e32 v145, v141, v141
	v_fmac_f32_e32 v116, v127, v127
	v_fmac_f32_e32 v117, v129, v129
	v_fmac_f32_e32 v126, v123, v123
	v_fmac_f32_e32 v128, v124, v124
	v_fmac_f32_e32 v142, v119, v119
	v_fmac_f32_e32 v143, v121, v121
	v_fmac_f32_e32 v144, v139, v139
	v_fmac_f32_e32 v145, v140, v140
	v_add_f32_e32 v116, v117, v116
	v_add_f32_e32 v117, v128, v126
	v_add_f32_e32 v126, v143, v142
	v_add_f32_e32 v127, v145, v144
	v_add_f32_e32 v116, v117, v116
	v_add_f32_e32 v117, v127, v126
	v_add_f32_e32 v126, v116, v117
	ds_bpermute_b32 v127, v170, v126
	v_cvt_pk_bf16_f32 v116, v122, v123
	v_cvt_pk_bf16_f32 v117, v124, v125
	global_store_dwordx4 v[164:165], v[114:117], off
	s_waitcnt lgkmcnt(0)
	s_nop 0
	v_add_f32_e32 v114, v126, v127
	v_lshlrev_b32_e32 v126, 2, v171
	ds_bpermute_b32 v115, v126, v114
	v_cvt_pk_bf16_f32 v116, v118, v119
	v_cvt_pk_bf16_f32 v117, v120, v121
	v_cvt_pk_bf16_f32 v118, v138, v139
	v_cvt_pk_bf16_f32 v119, v140, v141
	global_store_dwordx4 v[164:165], v[116:119], off offset:256
	s_and_saveexec_b64 s[20:21], s[0:1]
	s_cbranch_execz .LBB0_942
	v_lshlrev_b64 v[116:117], 7, v[156:157]
	v_lshl_add_u64 v[116:117], s[6:7], 0, v[116:117]
	v_lshl_add_u64 v[116:117], s[18:19], 2, v[116:117]
	s_lshl_b32 s94, s44, 2
	v_lshl_add_u64 v[116:117], v[116:117], 0, s[94:95]
	s_waitcnt lgkmcnt(0)
	v_add_f32_e32 v114, v114, v115
	global_store_dword v[116:117], v114, off

.LBB0_1040:
	s_add_i32 s51, 0, 0x10000
	s_add_i32 s54, 0, 0x14000
	v_add_u32_e32 v156, s51, v145
	v_add_u32_e32 v172, s54, v145
	ds_read_b128 v[140:143], v156
	ds_read_b128 v[148:151], v156 offset:1024
	ds_read_b128 v[152:155], v156 offset:2048
	ds_read_b128 v[156:159], v156 offset:3072
	ds_read_b128 v[160:163], v172
	ds_read_b128 v[164:167], v172 offset:1024
	ds_read_b128 v[168:171], v172 offset:2048
	ds_read_b128 v[172:175], v172 offset:3072
	s_add_u32 s22, s20, 0xfffc0080
	s_addc_u32 s23, s21, -1
	s_cmp_eq_u32 s50, 12
	s_cselect_b32 s25, s13, s23
	s_cselect_b32 s24, s46, s22
	s_cselect_b32 s23, s11, s49
	s_cselect_b32 s22, s47, s48
	v_lshl_add_u64 v[192:193], s[20:21], 0, v[136:137]
	s_add_i32 m0, s19, 0xc000
	ds_read_b128 v[176:179], v147
	ds_read_b128 v[180:183], v147 offset:1024
	ds_read_b128 v[184:187], v147 offset:2048
	ds_read_b128 v[188:191], v147 offset:3072
	ds_read_b128 v[202:205], v147 offset:4096
	ds_read_b128 v[206:209], v147 offset:5120
	ds_read_b128 v[210:213], v147 offset:6144
	ds_read_b128 v[214:217], v147 offset:7168
	global_load_lds_dwordx4 v[192:193], off
	v_lshl_add_u64 v[192:193], s[20:21], 0, v[138:139]
	s_add_i32 m0, s19, 0xe000
	s_nop 0
	global_load_lds_dwordx4 v[192:193], off
	s_waitcnt vmcnt(8)
	s_waitcnt lgkmcnt(0)
	s_barrier
	s_waitcnt lgkmcnt(0)
	v_mfma_f32_16x16x32_bf16 v[126:129], v[140:143], v[176:179], v[126:129]
	v_mfma_f32_16x16x32_bf16 v[122:125], v[152:155], v[176:179], v[122:125]
	v_mfma_f32_16x16x32_bf16 v[110:113], v[140:143], v[184:187], v[110:113]
	v_mfma_f32_16x16x32_bf16 v[106:109], v[152:155], v[184:187], v[106:109]
	v_mfma_f32_16x16x32_bf16 v[94:97], v[140:143], v[202:205], v[94:97]
	v_mfma_f32_16x16x32_bf16 v[90:93], v[152:155], v[202:205], v[90:93]
	v_mfma_f32_16x16x32_bf16 v[78:81], v[140:143], v[210:213], v[78:81]
	v_mfma_f32_16x16x32_bf16 v[74:77], v[152:155], v[210:213], v[74:77]
	v_mfma_f32_16x16x32_bf16 v[126:129], v[148:151], v[180:183], v[126:129]
	v_mfma_f32_16x16x32_bf16 v[122:125], v[156:159], v[180:183], v[122:125]
	v_mfma_f32_16x16x32_bf16 v[110:113], v[148:151], v[188:191], v[110:113]
	v_mfma_f32_16x16x32_bf16 v[106:109], v[156:159], v[188:191], v[106:109]
	v_mfma_f32_16x16x32_bf16 v[94:97], v[148:151], v[206:209], v[94:97]
	v_mfma_f32_16x16x32_bf16 v[90:93], v[156:159], v[206:209], v[90:93]
	v_mfma_f32_16x16x32_bf16 v[78:81], v[148:151], v[214:217], v[78:81]
	v_mfma_f32_16x16x32_bf16 v[74:77], v[156:159], v[214:217], v[74:77]
	v_mfma_f32_16x16x32_bf16 v[118:121], v[160:163], v[176:179], v[118:121]
	v_mfma_f32_16x16x32_bf16 v[114:117], v[168:171], v[176:179], v[114:117]
	v_mfma_f32_16x16x32_bf16 v[102:105], v[160:163], v[184:187], v[102:105]
	v_mfma_f32_16x16x32_bf16 v[98:101], v[168:171], v[184:187], v[98:101]
	v_mfma_f32_16x16x32_bf16 v[86:89], v[160:163], v[202:205], v[86:89]
	v_mfma_f32_16x16x32_bf16 v[82:85], v[168:171], v[202:205], v[82:85]
	v_mfma_f32_16x16x32_bf16 v[70:73], v[160:163], v[210:213], v[70:73]
	v_mfma_f32_16x16x32_bf16 v[66:69], v[168:171], v[210:213], v[66:69]
	v_mfma_f32_16x16x32_bf16 v[118:121], v[164:167], v[180:183], v[118:121]
	v_mfma_f32_16x16x32_bf16 v[114:117], v[172:175], v[180:183], v[114:117]
	v_mfma_f32_16x16x32_bf16 v[102:105], v[164:167], v[188:191], v[102:105]
	v_mfma_f32_16x16x32_bf16 v[98:101], v[172:175], v[188:191], v[98:101]
	v_mfma_f32_16x16x32_bf16 v[86:89], v[164:167], v[206:209], v[86:89]
	v_mfma_f32_16x16x32_bf16 v[82:85], v[172:175], v[206:209], v[82:85]
	v_mfma_f32_16x16x32_bf16 v[70:73], v[164:167], v[214:217], v[70:73]
	v_mfma_f32_16x16x32_bf16 v[66:69], v[172:175], v[214:217], v[66:69]
	s_barrier
	s_add_i32 s51, s51, s36
	v_lshl_add_u64 v[192:193], s[22:23], 0, v[194:195]
	s_mov_b32 m0, s51
	ds_read_b128 v[176:179], v147 offset:16384
	ds_read_b128 v[180:183], v147 offset:17408
	ds_read_b128 v[184:187], v147 offset:18432
	ds_read_b128 v[188:191], v147 offset:19456
	ds_read_b128 v[202:205], v147 offset:20480
	ds_read_b128 v[206:209], v147 offset:21504
	ds_read_b128 v[210:213], v147 offset:22528
	ds_read_b128 v[214:217], v147 offset:23552
	global_load_lds_dwordx4 v[192:193], off
	s_add_i32 m0, s51, 0x2000
	s_add_u32 s52, s22, 0x40000
	v_lshl_add_u64 v[218:219], s[22:23], 0, v[134:135]
	s_addc_u32 s53, s23, 0
	s_add_i32 s51, s54, s36
	global_load_lds_dwordx4 v[218:219], off
	v_lshl_add_u64 v[220:221], s[52:53], 0, v[194:195]
	s_mov_b32 m0, s51
	v_lshl_add_u64 v[222:223], s[24:25], 0, v[132:133]
	global_load_lds_dwordx4 v[220:221], off
	v_lshl_add_u64 v[220:221], s[52:53], 0, v[134:135]
	s_add_i32 m0, s51, 0x2000
	s_nop 0
	global_load_lds_dwordx4 v[220:221], off
	v_lshl_add_u64 v[220:221], s[24:25], 0, v[130:131]
	s_mov_b32 m0, s19
	s_nop 0
	global_load_lds_dwordx4 v[220:221], off
	s_mov_b32 m0, s37
	s_nop 0
	global_load_lds_dwordx4 v[222:223], off
	s_waitcnt vmcnt(8)
	s_waitcnt lgkmcnt(0)
	s_barrier
	s_waitcnt lgkmcnt(0)
	v_mfma_f32_16x16x32_bf16 v[62:65], v[140:143], v[176:179], v[62:65]
	v_mfma_f32_16x16x32_bf16 v[58:61], v[152:155], v[176:179], v[58:61]
	v_mfma_f32_16x16x32_bf16 v[46:49], v[140:143], v[184:187], v[46:49]
	v_mfma_f32_16x16x32_bf16 v[42:45], v[152:155], v[184:187], v[42:45]
	v_mfma_f32_16x16x32_bf16 v[30:33], v[140:143], v[202:205], v[30:33]
	v_mfma_f32_16x16x32_bf16 v[26:29], v[152:155], v[202:205], v[26:29]
	v_mfma_f32_16x16x32_bf16 v[14:17], v[140:143], v[210:213], v[14:17]
	v_mfma_f32_16x16x32_bf16 v[10:13], v[152:155], v[210:213], v[10:13]
	v_mfma_f32_16x16x32_bf16 v[62:65], v[148:151], v[180:183], v[62:65]
	v_mfma_f32_16x16x32_bf16 v[58:61], v[156:159], v[180:183], v[58:61]
	v_mfma_f32_16x16x32_bf16 v[46:49], v[148:151], v[188:191], v[46:49]
	v_mfma_f32_16x16x32_bf16 v[42:45], v[156:159], v[188:191], v[42:45]
	v_mfma_f32_16x16x32_bf16 v[30:33], v[148:151], v[206:209], v[30:33]
	v_mfma_f32_16x16x32_bf16 v[26:29], v[156:159], v[206:209], v[26:29]
	v_mfma_f32_16x16x32_bf16 v[14:17], v[148:151], v[214:217], v[14:17]
	v_mfma_f32_16x16x32_bf16 v[10:13], v[156:159], v[214:217], v[10:13]
	v_mfma_f32_16x16x32_bf16 v[54:57], v[160:163], v[176:179], v[54:57]
	v_mfma_f32_16x16x32_bf16 v[50:53], v[168:171], v[176:179], v[50:53]
	v_mfma_f32_16x16x32_bf16 v[38:41], v[160:163], v[184:187], v[38:41]
	v_mfma_f32_16x16x32_bf16 v[34:37], v[168:171], v[184:187], v[34:37]
	v_mfma_f32_16x16x32_bf16 v[22:25], v[160:163], v[202:205], v[22:25]
	v_mfma_f32_16x16x32_bf16 v[18:21], v[168:171], v[202:205], v[18:21]
	v_mfma_f32_16x16x32_bf16 v[6:9], v[160:163], v[210:213], v[6:9]
	v_mfma_f32_16x16x32_bf16 v[2:5], v[168:171], v[210:213], v[2:5]
	v_mfma_f32_16x16x32_bf16 v[54:57], v[164:167], v[180:183], v[54:57]
	v_mfma_f32_16x16x32_bf16 v[50:53], v[172:175], v[180:183], v[50:53]
	v_mfma_f32_16x16x32_bf16 v[38:41], v[164:167], v[188:191], v[38:41]
	v_mfma_f32_16x16x32_bf16 v[34:37], v[172:175], v[188:191], v[34:37]
	v_mfma_f32_16x16x32_bf16 v[22:25], v[164:167], v[206:209], v[22:25]
	v_mfma_f32_16x16x32_bf16 v[18:21], v[172:175], v[206:209], v[18:21]
	v_mfma_f32_16x16x32_bf16 v[6:9], v[164:167], v[214:217], v[6:9]
	v_mfma_f32_16x16x32_bf16 v[2:5], v[172:175], v[214:217], v[2:5]
	s_barrier
	s_add_i32 s51, 0, 0x18000
	s_add_i32 s52, 0, 0x1c000
	v_add_u32_e32 v156, s51, v145
	v_add_u32_e32 v172, s52, v145
	ds_read_b128 v[140:143], v156
	ds_read_b128 v[148:151], v156 offset:1024
	ds_read_b128 v[152:155], v156 offset:2048
	ds_read_b128 v[156:159], v156 offset:3072
	ds_read_b128 v[160:163], v172
	ds_read_b128 v[164:167], v172 offset:1024
	ds_read_b128 v[168:171], v172 offset:2048
	ds_read_b128 v[172:175], v172 offset:3072
	s_add_u32 s24, s24, 0x40000
	s_addc_u32 s25, s25, 0
	s_mov_b32 m0, s38
	v_lshl_add_u64 v[224:225], s[24:25], 0, v[130:131]
	ds_read_b128 v[176:179], v147 offset:32768
	ds_read_b128 v[180:183], v147 offset:33792
	ds_read_b128 v[184:187], v147 offset:34816
	ds_read_b128 v[188:191], v147 offset:35840
	ds_read_b128 v[202:205], v147 offset:36864
	ds_read_b128 v[206:209], v147 offset:37888
	ds_read_b128 v[210:213], v147 offset:38912
	ds_read_b128 v[214:217], v147 offset:39936
	global_load_lds_dwordx4 v[224:225], off
	v_lshl_add_u64 v[224:225], s[24:25], 0, v[132:133]
	s_mov_b32 m0, s39
	s_nop 0
	global_load_lds_dwordx4 v[224:225], off
	s_waitcnt vmcnt(8)
	s_waitcnt lgkmcnt(0)
	s_barrier
	s_waitcnt lgkmcnt(0)
	v_mfma_f32_16x16x32_bf16 v[126:129], v[140:143], v[176:179], v[126:129]
	v_mfma_f32_16x16x32_bf16 v[122:125], v[152:155], v[176:179], v[122:125]
	v_mfma_f32_16x16x32_bf16 v[110:113], v[140:143], v[184:187], v[110:113]
	v_mfma_f32_16x16x32_bf16 v[106:109], v[152:155], v[184:187], v[106:109]
	v_mfma_f32_16x16x32_bf16 v[94:97], v[140:143], v[202:205], v[94:97]
	v_mfma_f32_16x16x32_bf16 v[90:93], v[152:155], v[202:205], v[90:93]
	v_mfma_f32_16x16x32_bf16 v[78:81], v[140:143], v[210:213], v[78:81]
	v_mfma_f32_16x16x32_bf16 v[74:77], v[152:155], v[210:213], v[74:77]
	v_mfma_f32_16x16x32_bf16 v[126:129], v[148:151], v[180:183], v[126:129]
	v_mfma_f32_16x16x32_bf16 v[122:125], v[156:159], v[180:183], v[122:125]
	v_mfma_f32_16x16x32_bf16 v[110:113], v[148:151], v[188:191], v[110:113]
	v_mfma_f32_16x16x32_bf16 v[106:109], v[156:159], v[188:191], v[106:109]
	v_mfma_f32_16x16x32_bf16 v[94:97], v[148:151], v[206:209], v[94:97]
	v_mfma_f32_16x16x32_bf16 v[90:93], v[156:159], v[206:209], v[90:93]
	v_mfma_f32_16x16x32_bf16 v[78:81], v[148:151], v[214:217], v[78:81]
	v_mfma_f32_16x16x32_bf16 v[74:77], v[156:159], v[214:217], v[74:77]
	v_mfma_f32_16x16x32_bf16 v[118:121], v[160:163], v[176:179], v[118:121]
	v_mfma_f32_16x16x32_bf16 v[114:117], v[168:171], v[176:179], v[114:117]
	v_mfma_f32_16x16x32_bf16 v[102:105], v[160:163], v[184:187], v[102:105]
	v_mfma_f32_16x16x32_bf16 v[98:101], v[168:171], v[184:187], v[98:101]
	v_mfma_f32_16x16x32_bf16 v[86:89], v[160:163], v[202:205], v[86:89]
	v_mfma_f32_16x16x32_bf16 v[82:85], v[168:171], v[202:205], v[82:85]
	v_mfma_f32_16x16x32_bf16 v[70:73], v[160:163], v[210:213], v[70:73]
	v_mfma_f32_16x16x32_bf16 v[66:69], v[168:171], v[210:213], v[66:69]
	v_mfma_f32_16x16x32_bf16 v[118:121], v[164:167], v[180:183], v[118:121]
	v_mfma_f32_16x16x32_bf16 v[114:117], v[172:175], v[180:183], v[114:117]
	v_mfma_f32_16x16x32_bf16 v[102:105], v[164:167], v[188:191], v[102:105]
	v_mfma_f32_16x16x32_bf16 v[98:101], v[172:175], v[188:191], v[98:101]
	v_mfma_f32_16x16x32_bf16 v[86:89], v[164:167], v[206:209], v[86:89]
	v_mfma_f32_16x16x32_bf16 v[82:85], v[172:175], v[206:209], v[82:85]
	v_mfma_f32_16x16x32_bf16 v[70:73], v[164:167], v[214:217], v[70:73]
	v_mfma_f32_16x16x32_bf16 v[66:69], v[172:175], v[214:217], v[66:69]
	s_barrier
	s_add_i32 s24, s51, s36
	v_lshl_add_u64 v[192:193], v[192:193], 0, s[92:93]
	s_mov_b32 m0, s24
	ds_read_b128 v[176:179], v147 offset:49152
	ds_read_b128 v[180:183], v147 offset:50176
	ds_read_b128 v[184:187], v147 offset:51200
	ds_read_b128 v[188:191], v147 offset:52224
	ds_read_b128 v[202:205], v147 offset:53248
	ds_read_b128 v[206:209], v147 offset:54272
	ds_read_b128 v[210:213], v147 offset:55296
	ds_read_b128 v[214:217], v147 offset:56320
	global_load_lds_dwordx4 v[192:193], off
	s_add_i32 m0, s24, 0x2000
	s_add_u32 s22, s22, 0x40080
	v_lshl_add_u64 v[192:193], v[218:219], 0, s[92:93]
	s_addc_u32 s23, s23, 0
	s_add_i32 s24, s52, s36
	global_load_lds_dwordx4 v[192:193], off
	v_lshl_add_u64 v[192:193], s[22:23], 0, v[194:195]
	s_mov_b32 m0, s24
	s_nop 0
	global_load_lds_dwordx4 v[192:193], off
	v_lshl_add_u64 v[192:193], s[22:23], 0, v[134:135]
	s_add_i32 m0, s24, 0x2000
	s_nop 0
	global_load_lds_dwordx4 v[192:193], off
	v_lshl_add_u64 v[192:193], v[220:221], 0, s[92:93]
	s_mov_b32 m0, s42
	s_nop 0
	global_load_lds_dwordx4 v[192:193], off
	v_lshl_add_u64 v[192:193], v[222:223], 0, s[92:93]
	s_mov_b32 m0, s43
	s_nop 0
	global_load_lds_dwordx4 v[192:193], off
	s_waitcnt vmcnt(8)
	s_waitcnt lgkmcnt(0)
	s_barrier
	s_waitcnt lgkmcnt(0)
	v_mfma_f32_16x16x32_bf16 v[62:65], v[140:143], v[176:179], v[62:65]
	v_mfma_f32_16x16x32_bf16 v[58:61], v[152:155], v[176:179], v[58:61]
	v_mfma_f32_16x16x32_bf16 v[46:49], v[140:143], v[184:187], v[46:49]
	v_mfma_f32_16x16x32_bf16 v[42:45], v[152:155], v[184:187], v[42:45]
	v_mfma_f32_16x16x32_bf16 v[30:33], v[140:143], v[202:205], v[30:33]
	v_mfma_f32_16x16x32_bf16 v[26:29], v[152:155], v[202:205], v[26:29]
	v_mfma_f32_16x16x32_bf16 v[14:17], v[140:143], v[210:213], v[14:17]
	v_mfma_f32_16x16x32_bf16 v[10:13], v[152:155], v[210:213], v[10:13]
	v_mfma_f32_16x16x32_bf16 v[62:65], v[148:151], v[180:183], v[62:65]
	v_mfma_f32_16x16x32_bf16 v[58:61], v[156:159], v[180:183], v[58:61]
	v_mfma_f32_16x16x32_bf16 v[46:49], v[148:151], v[188:191], v[46:49]
	v_mfma_f32_16x16x32_bf16 v[42:45], v[156:159], v[188:191], v[42:45]
	v_mfma_f32_16x16x32_bf16 v[30:33], v[148:151], v[206:209], v[30:33]
	v_mfma_f32_16x16x32_bf16 v[26:29], v[156:159], v[206:209], v[26:29]
	v_mfma_f32_16x16x32_bf16 v[14:17], v[148:151], v[214:217], v[14:17]
	v_mfma_f32_16x16x32_bf16 v[10:13], v[156:159], v[214:217], v[10:13]
	v_mfma_f32_16x16x32_bf16 v[54:57], v[160:163], v[176:179], v[54:57]
	v_mfma_f32_16x16x32_bf16 v[50:53], v[168:171], v[176:179], v[50:53]
	v_mfma_f32_16x16x32_bf16 v[38:41], v[160:163], v[184:187], v[38:41]
	v_mfma_f32_16x16x32_bf16 v[34:37], v[168:171], v[184:187], v[34:37]
	v_mfma_f32_16x16x32_bf16 v[22:25], v[160:163], v[202:205], v[22:25]
	v_mfma_f32_16x16x32_bf16 v[18:21], v[168:171], v[202:205], v[18:21]
	v_mfma_f32_16x16x32_bf16 v[6:9], v[160:163], v[210:213], v[6:9]
	v_mfma_f32_16x16x32_bf16 v[2:5], v[168:171], v[210:213], v[2:5]
	v_mfma_f32_16x16x32_bf16 v[54:57], v[164:167], v[180:183], v[54:57]
	v_mfma_f32_16x16x32_bf16 v[50:53], v[172:175], v[180:183], v[50:53]
	v_mfma_f32_16x16x32_bf16 v[38:41], v[164:167], v[188:191], v[38:41]
	v_mfma_f32_16x16x32_bf16 v[34:37], v[172:175], v[188:191], v[34:37]
	v_mfma_f32_16x16x32_bf16 v[22:25], v[164:167], v[206:209], v[22:25]
	v_mfma_f32_16x16x32_bf16 v[18:21], v[172:175], v[206:209], v[18:21]
	v_mfma_f32_16x16x32_bf16 v[6:9], v[164:167], v[214:217], v[6:9]
	v_mfma_f32_16x16x32_bf16 v[2:5], v[172:175], v[214:217], v[2:5]
	s_add_i32 s50, s50, 2
	s_add_u32 s20, s20, 0x100
	s_addc_u32 s21, s21, 0
	s_add_u32 s48, s48, 0x100
	s_addc_u32 s49, s49, 0
	s_cmp_gt_u32 s50, 13
	s_barrier
	s_cbranch_scc0 .LBB0_1040
	s_and_b64 vcc, exec, s[8:9]
	s_cbranch_vccz .LBB0_1043
	s_barrier

.LBB0_1130:
	s_add_i32 s56, 0, 0x10000
	s_add_i32 s58, 0, 0x14000
	v_add_u32_e32 v152, s56, v167
	v_add_u32_e32 v164, s58, v167
	ds_read_b128 v[130:133], v152
	ds_read_b128 v[134:137], v152 offset:1024
	ds_read_b128 v[138:141], v152 offset:2048
	ds_read_b128 v[152:155], v152 offset:3072
	ds_read_b128 v[156:159], v164
	ds_read_b128 v[160:163], v164 offset:1024
	ds_read_b128 v[170:173], v164 offset:2048
	ds_read_b128 v[174:177], v164 offset:3072
	s_add_u32 s28, s26, 0xfff00080
	s_addc_u32 s29, s27, -1
	s_cmp_eq_u32 s55, 60
	s_cselect_b32 s31, s7, s29
	s_cselect_b32 s30, s9, s28
	s_cselect_b32 s29, s19, s54
	s_cselect_b32 s28, s21, s53
	v_lshl_add_u64 v[164:165], s[26:27], 0, v[148:149]
	s_add_i32 m0, s44, 0xc000
	ds_read_b128 v[178:181], v169
	ds_read_b128 v[182:185], v169 offset:1024
	ds_read_b128 v[186:189], v169 offset:2048
	ds_read_b128 v[190:193], v169 offset:3072
	ds_read_b128 v[202:205], v169 offset:4096
	ds_read_b128 v[206:209], v169 offset:5120
	ds_read_b128 v[210:213], v169 offset:6144
	ds_read_b128 v[214:217], v169 offset:7168
	global_load_lds_dwordx4 v[164:165], off
	v_lshl_add_u64 v[164:165], s[26:27], 0, v[150:151]
	s_add_i32 m0, s44, 0xe000
	s_nop 0
	global_load_lds_dwordx4 v[164:165], off
	s_waitcnt vmcnt(8)
	s_waitcnt lgkmcnt(0)
	s_barrier
	s_waitcnt lgkmcnt(0)
	v_mfma_f32_16x16x32_bf16 v[126:129], v[130:133], v[178:181], v[126:129]
	v_mfma_f32_16x16x32_bf16 v[122:125], v[138:141], v[178:181], v[122:125]
	v_mfma_f32_16x16x32_bf16 v[110:113], v[130:133], v[186:189], v[110:113]
	v_mfma_f32_16x16x32_bf16 v[106:109], v[138:141], v[186:189], v[106:109]
	v_mfma_f32_16x16x32_bf16 v[94:97], v[130:133], v[202:205], v[94:97]
	v_mfma_f32_16x16x32_bf16 v[90:93], v[138:141], v[202:205], v[90:93]
	v_mfma_f32_16x16x32_bf16 v[78:81], v[130:133], v[210:213], v[78:81]
	v_mfma_f32_16x16x32_bf16 v[74:77], v[138:141], v[210:213], v[74:77]
	v_mfma_f32_16x16x32_bf16 v[126:129], v[134:137], v[182:185], v[126:129]
	v_mfma_f32_16x16x32_bf16 v[122:125], v[152:155], v[182:185], v[122:125]
	v_mfma_f32_16x16x32_bf16 v[110:113], v[134:137], v[190:193], v[110:113]
	v_mfma_f32_16x16x32_bf16 v[106:109], v[152:155], v[190:193], v[106:109]
	v_mfma_f32_16x16x32_bf16 v[94:97], v[134:137], v[206:209], v[94:97]
	v_mfma_f32_16x16x32_bf16 v[90:93], v[152:155], v[206:209], v[90:93]
	v_mfma_f32_16x16x32_bf16 v[78:81], v[134:137], v[214:217], v[78:81]
	v_mfma_f32_16x16x32_bf16 v[74:77], v[152:155], v[214:217], v[74:77]
	v_mfma_f32_16x16x32_bf16 v[118:121], v[156:159], v[178:181], v[118:121]
	v_mfma_f32_16x16x32_bf16 v[114:117], v[170:173], v[178:181], v[114:117]
	v_mfma_f32_16x16x32_bf16 v[102:105], v[156:159], v[186:189], v[102:105]
	v_mfma_f32_16x16x32_bf16 v[98:101], v[170:173], v[186:189], v[98:101]
	v_mfma_f32_16x16x32_bf16 v[86:89], v[156:159], v[202:205], v[86:89]
	v_mfma_f32_16x16x32_bf16 v[82:85], v[170:173], v[202:205], v[82:85]
	v_mfma_f32_16x16x32_bf16 v[70:73], v[156:159], v[210:213], v[70:73]
	v_mfma_f32_16x16x32_bf16 v[66:69], v[170:173], v[210:213], v[66:69]
	v_mfma_f32_16x16x32_bf16 v[118:121], v[160:163], v[182:185], v[118:121]
	v_mfma_f32_16x16x32_bf16 v[114:117], v[174:177], v[182:185], v[114:117]
	v_mfma_f32_16x16x32_bf16 v[102:105], v[160:163], v[190:193], v[102:105]
	v_mfma_f32_16x16x32_bf16 v[98:101], v[174:177], v[190:193], v[98:101]
	v_mfma_f32_16x16x32_bf16 v[86:89], v[160:163], v[206:209], v[86:89]
	v_mfma_f32_16x16x32_bf16 v[82:85], v[174:177], v[206:209], v[82:85]
	v_mfma_f32_16x16x32_bf16 v[70:73], v[160:163], v[214:217], v[70:73]
	v_mfma_f32_16x16x32_bf16 v[66:69], v[174:177], v[214:217], v[66:69]
	s_barrier
	s_add_i32 s56, s56, s43
	v_lshl_add_u64 v[164:165], s[28:29], 0, v[194:195]
	s_mov_b32 m0, s56
	ds_read_b128 v[178:181], v169 offset:16384
	ds_read_b128 v[182:185], v169 offset:17408
	ds_read_b128 v[186:189], v169 offset:18432
	ds_read_b128 v[190:193], v169 offset:19456
	ds_read_b128 v[202:205], v169 offset:20480
	ds_read_b128 v[206:209], v169 offset:21504
	ds_read_b128 v[210:213], v169 offset:22528
	ds_read_b128 v[214:217], v169 offset:23552
	global_load_lds_dwordx4 v[164:165], off
	s_add_i32 m0, s56, 0x2000
	s_add_u32 s56, s28, 0x100000
	v_lshl_add_u64 v[218:219], s[28:29], 0, v[146:147]
	s_addc_u32 s57, s29, 0
	s_add_i32 s58, s58, s43
	global_load_lds_dwordx4 v[218:219], off
	v_lshl_add_u64 v[220:221], s[56:57], 0, v[194:195]
	s_mov_b32 m0, s58
	v_lshl_add_u64 v[222:223], s[30:31], 0, v[144:145]
	global_load_lds_dwordx4 v[220:221], off
	v_lshl_add_u64 v[220:221], s[56:57], 0, v[146:147]
	s_add_i32 m0, s58, 0x2000
	s_nop 0
	global_load_lds_dwordx4 v[220:221], off
	v_lshl_add_u64 v[220:221], s[30:31], 0, v[142:143]
	s_mov_b32 m0, s44
	s_nop 0
	global_load_lds_dwordx4 v[220:221], off
	s_mov_b32 m0, s45
	s_nop 0
	global_load_lds_dwordx4 v[222:223], off
	s_waitcnt vmcnt(8)
	s_waitcnt lgkmcnt(0)
	s_barrier
	s_waitcnt lgkmcnt(0)
	v_mfma_f32_16x16x32_bf16 v[62:65], v[130:133], v[178:181], v[62:65]
	v_mfma_f32_16x16x32_bf16 v[58:61], v[138:141], v[178:181], v[58:61]
	v_mfma_f32_16x16x32_bf16 v[46:49], v[130:133], v[186:189], v[46:49]
	v_mfma_f32_16x16x32_bf16 v[42:45], v[138:141], v[186:189], v[42:45]
	v_mfma_f32_16x16x32_bf16 v[30:33], v[130:133], v[202:205], v[30:33]
	v_mfma_f32_16x16x32_bf16 v[26:29], v[138:141], v[202:205], v[26:29]
	v_mfma_f32_16x16x32_bf16 v[14:17], v[130:133], v[210:213], v[14:17]
	v_mfma_f32_16x16x32_bf16 v[10:13], v[138:141], v[210:213], v[10:13]
	v_mfma_f32_16x16x32_bf16 v[62:65], v[134:137], v[182:185], v[62:65]
	v_mfma_f32_16x16x32_bf16 v[58:61], v[152:155], v[182:185], v[58:61]
	v_mfma_f32_16x16x32_bf16 v[46:49], v[134:137], v[190:193], v[46:49]
	v_mfma_f32_16x16x32_bf16 v[42:45], v[152:155], v[190:193], v[42:45]
	v_mfma_f32_16x16x32_bf16 v[30:33], v[134:137], v[206:209], v[30:33]
	v_mfma_f32_16x16x32_bf16 v[26:29], v[152:155], v[206:209], v[26:29]
	v_mfma_f32_16x16x32_bf16 v[14:17], v[134:137], v[214:217], v[14:17]
	v_mfma_f32_16x16x32_bf16 v[10:13], v[152:155], v[214:217], v[10:13]
	v_mfma_f32_16x16x32_bf16 v[54:57], v[156:159], v[178:181], v[54:57]
	v_mfma_f32_16x16x32_bf16 v[50:53], v[170:173], v[178:181], v[50:53]
	v_mfma_f32_16x16x32_bf16 v[38:41], v[156:159], v[186:189], v[38:41]
	v_mfma_f32_16x16x32_bf16 v[34:37], v[170:173], v[186:189], v[34:37]
	v_mfma_f32_16x16x32_bf16 v[22:25], v[156:159], v[202:205], v[22:25]
	v_mfma_f32_16x16x32_bf16 v[18:21], v[170:173], v[202:205], v[18:21]
	v_mfma_f32_16x16x32_bf16 v[6:9], v[156:159], v[210:213], v[6:9]
	v_mfma_f32_16x16x32_bf16 v[2:5], v[170:173], v[210:213], v[2:5]
	v_mfma_f32_16x16x32_bf16 v[54:57], v[160:163], v[182:185], v[54:57]
	v_mfma_f32_16x16x32_bf16 v[50:53], v[174:177], v[182:185], v[50:53]
	v_mfma_f32_16x16x32_bf16 v[38:41], v[160:163], v[190:193], v[38:41]
	v_mfma_f32_16x16x32_bf16 v[34:37], v[174:177], v[190:193], v[34:37]
	v_mfma_f32_16x16x32_bf16 v[22:25], v[160:163], v[206:209], v[22:25]
	v_mfma_f32_16x16x32_bf16 v[18:21], v[174:177], v[206:209], v[18:21]
	v_mfma_f32_16x16x32_bf16 v[6:9], v[160:163], v[214:217], v[6:9]
	v_mfma_f32_16x16x32_bf16 v[2:5], v[174:177], v[214:217], v[2:5]
	s_barrier
	s_add_i32 s56, 0, 0x18000
	s_add_i32 s57, 0, 0x1c000
	v_add_u32_e32 v152, s56, v167
	v_add_u32_e32 v174, s57, v167
	ds_read_b128 v[130:133], v152
	ds_read_b128 v[134:137], v152 offset:1024
	ds_read_b128 v[138:141], v152 offset:2048
	ds_read_b128 v[152:155], v152 offset:3072
	ds_read_b128 v[156:159], v174
	ds_read_b128 v[160:163], v174 offset:1024
	ds_read_b128 v[170:173], v174 offset:2048
	ds_read_b128 v[174:177], v174 offset:3072
	s_add_u32 s30, s30, 0x100000
	s_addc_u32 s31, s31, 0
	s_mov_b32 m0, s46
	v_lshl_add_u64 v[224:225], s[30:31], 0, v[142:143]
	ds_read_b128 v[178:181], v169 offset:32768
	ds_read_b128 v[182:185], v169 offset:33792
	ds_read_b128 v[186:189], v169 offset:34816
	ds_read_b128 v[190:193], v169 offset:35840
	ds_read_b128 v[202:205], v169 offset:36864
	ds_read_b128 v[206:209], v169 offset:37888
	ds_read_b128 v[210:213], v169 offset:38912
	ds_read_b128 v[214:217], v169 offset:39936
	global_load_lds_dwordx4 v[224:225], off
	v_lshl_add_u64 v[224:225], s[30:31], 0, v[144:145]
	s_mov_b32 m0, s47
	s_nop 0
	global_load_lds_dwordx4 v[224:225], off
	s_waitcnt vmcnt(8)
	s_waitcnt lgkmcnt(0)
	s_barrier
	s_waitcnt lgkmcnt(0)
	v_mfma_f32_16x16x32_bf16 v[126:129], v[130:133], v[178:181], v[126:129]
	v_mfma_f32_16x16x32_bf16 v[122:125], v[138:141], v[178:181], v[122:125]
	v_mfma_f32_16x16x32_bf16 v[110:113], v[130:133], v[186:189], v[110:113]
	v_mfma_f32_16x16x32_bf16 v[106:109], v[138:141], v[186:189], v[106:109]
	v_mfma_f32_16x16x32_bf16 v[94:97], v[130:133], v[202:205], v[94:97]
	v_mfma_f32_16x16x32_bf16 v[90:93], v[138:141], v[202:205], v[90:93]
	v_mfma_f32_16x16x32_bf16 v[78:81], v[130:133], v[210:213], v[78:81]
	v_mfma_f32_16x16x32_bf16 v[74:77], v[138:141], v[210:213], v[74:77]
	v_mfma_f32_16x16x32_bf16 v[126:129], v[134:137], v[182:185], v[126:129]
	v_mfma_f32_16x16x32_bf16 v[122:125], v[152:155], v[182:185], v[122:125]
	v_mfma_f32_16x16x32_bf16 v[110:113], v[134:137], v[190:193], v[110:113]
	v_mfma_f32_16x16x32_bf16 v[106:109], v[152:155], v[190:193], v[106:109]
	v_mfma_f32_16x16x32_bf16 v[94:97], v[134:137], v[206:209], v[94:97]
	v_mfma_f32_16x16x32_bf16 v[90:93], v[152:155], v[206:209], v[90:93]
	v_mfma_f32_16x16x32_bf16 v[78:81], v[134:137], v[214:217], v[78:81]
	v_mfma_f32_16x16x32_bf16 v[74:77], v[152:155], v[214:217], v[74:77]
	v_mfma_f32_16x16x32_bf16 v[118:121], v[156:159], v[178:181], v[118:121]
	v_mfma_f32_16x16x32_bf16 v[114:117], v[170:173], v[178:181], v[114:117]
	v_mfma_f32_16x16x32_bf16 v[102:105], v[156:159], v[186:189], v[102:105]
	v_mfma_f32_16x16x32_bf16 v[98:101], v[170:173], v[186:189], v[98:101]
	v_mfma_f32_16x16x32_bf16 v[86:89], v[156:159], v[202:205], v[86:89]
	v_mfma_f32_16x16x32_bf16 v[82:85], v[170:173], v[202:205], v[82:85]
	v_mfma_f32_16x16x32_bf16 v[70:73], v[156:159], v[210:213], v[70:73]
	v_mfma_f32_16x16x32_bf16 v[66:69], v[170:173], v[210:213], v[66:69]
	v_mfma_f32_16x16x32_bf16 v[118:121], v[160:163], v[182:185], v[118:121]
	v_mfma_f32_16x16x32_bf16 v[114:117], v[174:177], v[182:185], v[114:117]
	v_mfma_f32_16x16x32_bf16 v[102:105], v[160:163], v[190:193], v[102:105]
	v_mfma_f32_16x16x32_bf16 v[98:101], v[174:177], v[190:193], v[98:101]
	v_mfma_f32_16x16x32_bf16 v[86:89], v[160:163], v[206:209], v[86:89]
	v_mfma_f32_16x16x32_bf16 v[82:85], v[174:177], v[206:209], v[82:85]
	v_mfma_f32_16x16x32_bf16 v[70:73], v[160:163], v[214:217], v[70:73]
	v_mfma_f32_16x16x32_bf16 v[66:69], v[174:177], v[214:217], v[66:69]
	s_barrier
	s_add_i32 s30, s56, s43
	v_lshl_add_u64 v[164:165], v[164:165], 0, s[92:93]
	s_mov_b32 m0, s30
	ds_read_b128 v[178:181], v169 offset:49152
	ds_read_b128 v[182:185], v169 offset:50176
	ds_read_b128 v[186:189], v169 offset:51200
	ds_read_b128 v[190:193], v169 offset:52224
	ds_read_b128 v[202:205], v169 offset:53248
	ds_read_b128 v[206:209], v169 offset:54272
	ds_read_b128 v[210:213], v169 offset:55296
	ds_read_b128 v[214:217], v169 offset:56320
	global_load_lds_dwordx4 v[164:165], off
	s_add_i32 m0, s30, 0x2000
	s_add_u32 s28, s28, 0x100080
	v_lshl_add_u64 v[164:165], v[218:219], 0, s[92:93]
	s_addc_u32 s29, s29, 0
	s_add_i32 s30, s57, s43
	global_load_lds_dwordx4 v[164:165], off
	v_lshl_add_u64 v[164:165], s[28:29], 0, v[194:195]
	s_mov_b32 m0, s30
	s_nop 0
	global_load_lds_dwordx4 v[164:165], off
	v_lshl_add_u64 v[164:165], s[28:29], 0, v[146:147]
	s_add_i32 m0, s30, 0x2000
	s_nop 0
	global_load_lds_dwordx4 v[164:165], off
	v_lshl_add_u64 v[164:165], v[220:221], 0, s[92:93]
	s_mov_b32 m0, s49
	s_nop 0
	global_load_lds_dwordx4 v[164:165], off
	v_lshl_add_u64 v[164:165], v[222:223], 0, s[92:93]
	s_mov_b32 m0, s50
	s_nop 0
	global_load_lds_dwordx4 v[164:165], off
	s_waitcnt vmcnt(8)
	s_waitcnt lgkmcnt(0)
	s_barrier
	s_waitcnt lgkmcnt(0)
	v_mfma_f32_16x16x32_bf16 v[62:65], v[130:133], v[178:181], v[62:65]
	v_mfma_f32_16x16x32_bf16 v[58:61], v[138:141], v[178:181], v[58:61]
	v_mfma_f32_16x16x32_bf16 v[46:49], v[130:133], v[186:189], v[46:49]
	v_mfma_f32_16x16x32_bf16 v[42:45], v[138:141], v[186:189], v[42:45]
	v_mfma_f32_16x16x32_bf16 v[30:33], v[130:133], v[202:205], v[30:33]
	v_mfma_f32_16x16x32_bf16 v[26:29], v[138:141], v[202:205], v[26:29]
	v_mfma_f32_16x16x32_bf16 v[14:17], v[130:133], v[210:213], v[14:17]
	v_mfma_f32_16x16x32_bf16 v[10:13], v[138:141], v[210:213], v[10:13]
	v_mfma_f32_16x16x32_bf16 v[62:65], v[134:137], v[182:185], v[62:65]
	v_mfma_f32_16x16x32_bf16 v[58:61], v[152:155], v[182:185], v[58:61]
	v_mfma_f32_16x16x32_bf16 v[46:49], v[134:137], v[190:193], v[46:49]
	v_mfma_f32_16x16x32_bf16 v[42:45], v[152:155], v[190:193], v[42:45]
	v_mfma_f32_16x16x32_bf16 v[30:33], v[134:137], v[206:209], v[30:33]
	v_mfma_f32_16x16x32_bf16 v[26:29], v[152:155], v[206:209], v[26:29]
	v_mfma_f32_16x16x32_bf16 v[14:17], v[134:137], v[214:217], v[14:17]
	v_mfma_f32_16x16x32_bf16 v[10:13], v[152:155], v[214:217], v[10:13]
	v_mfma_f32_16x16x32_bf16 v[54:57], v[156:159], v[178:181], v[54:57]
	v_mfma_f32_16x16x32_bf16 v[50:53], v[170:173], v[178:181], v[50:53]
	v_mfma_f32_16x16x32_bf16 v[38:41], v[156:159], v[186:189], v[38:41]
	v_mfma_f32_16x16x32_bf16 v[34:37], v[170:173], v[186:189], v[34:37]
	v_mfma_f32_16x16x32_bf16 v[22:25], v[156:159], v[202:205], v[22:25]
	v_mfma_f32_16x16x32_bf16 v[18:21], v[170:173], v[202:205], v[18:21]
	v_mfma_f32_16x16x32_bf16 v[6:9], v[156:159], v[210:213], v[6:9]
	v_mfma_f32_16x16x32_bf16 v[2:5], v[170:173], v[210:213], v[2:5]
	v_mfma_f32_16x16x32_bf16 v[54:57], v[160:163], v[182:185], v[54:57]
	v_mfma_f32_16x16x32_bf16 v[50:53], v[174:177], v[182:185], v[50:53]
	v_mfma_f32_16x16x32_bf16 v[38:41], v[160:163], v[190:193], v[38:41]
	v_mfma_f32_16x16x32_bf16 v[34:37], v[174:177], v[190:193], v[34:37]
	v_mfma_f32_16x16x32_bf16 v[22:25], v[160:163], v[206:209], v[22:25]
	v_mfma_f32_16x16x32_bf16 v[18:21], v[174:177], v[206:209], v[18:21]
	v_mfma_f32_16x16x32_bf16 v[6:9], v[160:163], v[214:217], v[6:9]
	v_mfma_f32_16x16x32_bf16 v[2:5], v[174:177], v[214:217], v[2:5]
	s_add_i32 s55, s55, 2
	s_add_u32 s26, s26, 0x100
	s_addc_u32 s27, s27, 0
	s_add_u32 s53, s53, 0x100
	s_addc_u32 s54, s54, 0
	s_cmp_gt_u32 s55, 61
	s_barrier
	s_cbranch_scc0 .LBB0_1130
	v_lshl_add_u32 v154, s6, 8, v166
	v_lshl_or_b32 v152, s8, 8, v168
	v_ashrrev_i32_e32 v155, 31, v154
	v_lshlrev_b64 v[130:131], 11, v[154:155]
	v_ashrrev_i32_e32 v153, 31, v152
	v_or_b32_e32 v156, 16, v154
	v_lshl_add_u64 v[130:131], s[12:13], 0, v[130:131]
	v_lshlrev_b64 v[132:133], 1, v[152:153]
	v_ashrrev_i32_e32 v157, 31, v156
	v_lshl_add_u64 v[160:161], v[130:131], 0, v[132:133]
	v_lshlrev_b64 v[130:131], 11, v[156:157]
	global_load_dwordx4 v[170:173], v[160:161], off
	global_load_dwordx4 v[138:141], v[160:161], off offset:256
	v_lshl_add_u64 v[130:131], s[12:13], 0, v[130:131]
	v_lshl_add_u64 v[158:159], v[130:131], 0, v[132:133]
	global_load_dwordx4 v[134:137], v[158:159], off
	global_load_dwordx4 v[130:133], v[158:159], off offset:256
	v_cndmask_b32_e64 v162, 0, 1, s[16:17]
	v_cmp_ne_u32_e64 s[6:7], 1, v162
	v_lshlrev_b64 v[162:163], 10, v[154:155]
	v_lshl_add_u64 v[162:163], v[162:163], 0, v[152:153]
	s_andn2_b64 vcc, exec, s[16:17]
	s_waitcnt vmcnt(0)
	v_lshlrev_b32_e32 v164, 16, v170
	v_and_b32_e32 v165, 0xffff0000, v170
	v_lshlrev_b32_e32 v170, 16, v171
	v_and_b32_e32 v171, 0xffff0000, v171
	v_lshlrev_b32_e32 v174, 16, v172
	v_and_b32_e32 v175, 0xffff0000, v172
	v_lshlrev_b32_e32 v172, 16, v173
	v_and_b32_e32 v173, 0xffff0000, v173
	v_pk_add_f32 v[126:127], v[126:127], v[164:165]
	v_pk_add_f32 v[128:129], v[128:129], v[170:171]
	v_pk_add_f32 v[122:123], v[122:123], v[174:175]
	v_pk_add_f32 v[124:125], v[124:125], v[172:173]
	v_lshl_add_u64 v[164:165], v[162:163], 2, s[14:15]
	s_cbranch_vccnz .LBB0_1210
	global_store_dwordx4 v[164:165], v[126:129], off
	global_store_dwordx4 v[164:165], v[122:125], off offset:16
	s_cbranch_execnz .LBB0_1134
